# S5 GEMM epilogue: u loads batched ahead of the gelu math (two batches of 16, counted waits) instead of 32 load-wait-store steps
# baseline (speedup 1.0000x reference)
; __device__ __forceinline__ float bflo(unsigned w) { return __uint_as_float(w << 16); }
; __device__ __forceinline__ float bfhi(unsigned w) { return __uint_as_float(w & 0xffff0000u); }
; __device__ __forceinline__ unsigned pk2(float lo, float hi) { return pg8::cvt_pk_bf16(lo, hi); }
; __device__ __forceinline__ float gelu_tanh(float y) { const float a = 0.7978845608028654f * (y + 0.044715f * y * y * y); const float e = __expf(2.0f * a); const float th = 1.0f - 2.0f * __builtin_amdgcn_rcpf(e + 1.0f); return 0.5f * y * (1.0f + th); }
;     __device__ __forceinline__ void operator()(const f32x4 (&acc)[2][2][4][2], const Unit& u, int wr, int wc, int fr, int fq) const {
;     ...
;             for (int m = 0; m < 4; ++m) { const int rowg = mh * 256 + ai * 128 + wr * 64 + m * 16 + fr, b = rowg >> 6, c = rowg & 63;
; #pragma unroll
;                 for (int bj = 0; bj < 2; ++bj)
; #pragma unroll
;                     for (int n = 0; n < 2; ++n) { const int colg = nh * 256 + bj * 128 + wc * 32 + n * 16 + 4 * fq, tau = colg >> 4, ch = g * 16 + (colg & 15);
;                         const size_t tok = (size_t)b * SEQ + 32 * c + tau;
;                         const u32x2 uw = *(const u32x2*)(z + tok * ZP + C_SU + ch); const f32x4 d4 = *(const f32x4*)(dsk + ch); const f32x4 a = acc[ai][bj][m][n];
;                         u32x2 o; o.x = pk2(gelu_tanh(a[0] + d4[0] * bflo(uw.x)), gelu_tanh(a[1] + d4[1] * bfhi(uw.x))); o.y = pk2(gelu_tanh(a[2] + d4[2] * bflo(uw.y)), gelu_tanh(a[3] + d4[3] * bfhi(uw.y)));
;                         *(u32x2*)(ysg + tok * 512 + ch) = o; } }
.LBB0_714:
	s_lshl_b32 s0, s1, 8
	s_and_b32 s0, s0, 0x100
	s_lshl_b32 s4, s40, 8
	s_add_i32 s0, s0, s31
	s_and_b32 s4, s4, 0x100
	s_or_b32 s6, s4, s34
	s_ashr_i32 s4, s0, 6
	s_ashr_i32 s5, s4, 31
	s_lshl_b64 s[20:21], s[4:5], 11
	s_lshl_b32 s1, s1, 3
	s_lshr_b32 s7, s6, 4
	v_and_or_b32 v148, s1, -16, v135
	s_or_b32 s5, s7, 1
	s_or_b32 s4, s7, 8
	s_or_b32 s6, s7, 9
	s_addk_i32 s0, 0x80
	s_ashr_i32 s0, s0, 6
	v_ashrrev_i32_e32 v149, 31, v148
	v_lshlrev_b32_e32 v146, 1, v148
	s_ashr_i32 s1, s0, 31
	v_lshl_add_u64 v[148:149], v[148:149], 2, s[12:13]
	s_lshl_b64 s[22:23], s[0:1], 11
	v_add_u32_e32 v147, s75, v146
	global_load_dwordx4 v[154:157], v[148:149], off
	v_or_b32_e32 v162, s20, v134
	v_or_b32_e32 v162, s7, v162
	v_mad_u32_u24 v162, v162, s88, v147
	global_load_dwordx2 v[162:163], v162, s[76:77]
	v_or_b32_e32 v164, s20, v134
	v_or_b32_e32 v164, s5, v164
	v_mad_u32_u24 v164, v164, s88, v147
	global_load_dwordx2 v[164:165], v164, s[76:77]
	v_or_b32_e32 v166, s20, v134
	v_or_b32_e32 v166, s4, v166
	v_mad_u32_u24 v166, v166, s88, v147
	global_load_dwordx2 v[166:167], v166, s[76:77]
	v_or_b32_e32 v168, s20, v134
	v_or_b32_e32 v168, s6, v168
	v_mad_u32_u24 v168, v168, s88, v147
	global_load_dwordx2 v[168:169], v168, s[76:77]
	v_or_b32_e32 v170, s20, v136
	v_or_b32_e32 v170, s7, v170
	v_mad_u32_u24 v170, v170, s88, v147
	global_load_dwordx2 v[170:171], v170, s[76:77]
	v_or_b32_e32 v172, s20, v136
	v_or_b32_e32 v172, s5, v172
	v_mad_u32_u24 v172, v172, s88, v147
	global_load_dwordx2 v[172:173], v172, s[76:77]
	v_or_b32_e32 v186, s20, v136
	v_or_b32_e32 v186, s4, v186
	v_mad_u32_u24 v186, v186, s88, v147
	global_load_dwordx2 v[186:187], v186, s[76:77]
	v_or_b32_e32 v188, s20, v136
	v_or_b32_e32 v188, s6, v188
	v_mad_u32_u24 v188, v188, s88, v147
	global_load_dwordx2 v[188:189], v188, s[76:77]
	v_or_b32_e32 v190, s20, v138
	v_or_b32_e32 v190, s7, v190
	v_mad_u32_u24 v190, v190, s88, v147
	global_load_dwordx2 v[190:191], v190, s[76:77]
	v_or_b32_e32 v192, s20, v138
	v_or_b32_e32 v192, s5, v192
	v_mad_u32_u24 v192, v192, s88, v147
	global_load_dwordx2 v[192:193], v192, s[76:77]
	v_or_b32_e32 v194, s20, v138
	v_or_b32_e32 v194, s4, v194
	v_mad_u32_u24 v194, v194, s88, v147
	global_load_dwordx2 v[194:195], v194, s[76:77]
	v_or_b32_e32 v196, s20, v138
	v_or_b32_e32 v196, s6, v196
	v_mad_u32_u24 v196, v196, s88, v147
	global_load_dwordx2 v[196:197], v196, s[76:77]
	v_or_b32_e32 v198, s20, v140
	v_or_b32_e32 v198, s7, v198
	v_mad_u32_u24 v198, v198, s88, v147
	global_load_dwordx2 v[198:199], v198, s[76:77]
	v_or_b32_e32 v200, s20, v140
	v_or_b32_e32 v200, s5, v200
	v_mad_u32_u24 v200, v200, s88, v147
	global_load_dwordx2 v[200:201], v200, s[76:77]
	v_or_b32_e32 v202, s20, v140
	v_or_b32_e32 v202, s4, v202
	v_mad_u32_u24 v202, v202, s88, v147
	global_load_dwordx2 v[202:203], v202, s[76:77]
	v_or_b32_e32 v204, s20, v140
	v_or_b32_e32 v204, s6, v204
	v_mad_u32_u24 v204, v204, s88, v147
	global_load_dwordx2 v[204:205], v204, s[76:77]
	s_waitcnt vmcnt(15)
	v_lshlrev_b32_e32 v150, 16, v162
	v_and_b32_e32 v151, 0xffff0000, v162
	v_lshlrev_b32_e32 v152, 16, v163
	v_and_b32_e32 v153, 0xffff0000, v163
	v_or_b32_e32 v139, s20, v134
	v_pk_fma_f32 v[128:129], v[154:155], v[150:151], v[128:129]
	v_pk_fma_f32 v[130:131], v[156:157], v[152:153], v[130:131]
	v_or_b32_e32 v139, s7, v139
	v_lshl_add_u32 v141, v139, 10, v146
	v_mul_f32_e32 v150, 0x3d372713, v128
	v_mul_f32_e32 v151, 0x3d372713, v129
	v_mul_f32_e32 v152, 0x3d372713, v130
	v_mul_f32_e32 v153, 0x3d372713, v131
	v_mul_f32_e32 v150, v128, v150
	v_mul_f32_e32 v151, v129, v151
	v_mul_f32_e32 v152, v130, v152
	v_mul_f32_e32 v153, v131, v153
	v_fma_f32 v150, v128, v150, v128
	v_fma_f32 v151, v129, v151, v129
	v_fma_f32 v152, v130, v152, v130
	v_fma_f32 v153, v131, v153, v131
	v_mul_f32_e32 v150, 0x3f4c422a, v150
	v_mul_f32_e32 v151, 0x3f4c422a, v151
	v_mul_f32_e32 v152, 0x3f4c422a, v152
	v_mul_f32_e32 v153, 0x3f4c422a, v153
	v_add_f32_e32 v150, v150, v150
	v_add_f32_e32 v151, v151, v151
	v_add_f32_e32 v152, v152, v152
	v_add_f32_e32 v153, v153, v153
	v_mul_f32_e32 v150, 0x3fb8aa3b, v150
	v_mul_f32_e32 v151, 0x3fb8aa3b, v151
	v_mul_f32_e32 v152, 0x3fb8aa3b, v152
	v_mul_f32_e32 v153, 0x3fb8aa3b, v153
	v_exp_f32_e32 v150, v150
	v_exp_f32_e32 v151, v151
	v_exp_f32_e32 v152, v152
	v_exp_f32_e32 v153, v153
	v_add_f32_e32 v150, 1.0, v150
	v_add_f32_e32 v151, 1.0, v151
	v_add_f32_e32 v152, 1.0, v152
	v_add_f32_e32 v153, 1.0, v153
	v_rcp_f32_e32 v150, v150
	v_rcp_f32_e32 v151, v151
	v_rcp_f32_e32 v152, v152
	v_rcp_f32_e32 v153, v153
	v_pk_mul_f32 v[128:129], v[128:129], 0.5 op_sel_hi:[1,0]
	v_pk_mul_f32 v[130:131], v[130:131], 0.5 op_sel_hi:[1,0]
	v_pk_fma_f32 v[150:151], v[150:151], 2.0, 1.0 op_sel_hi:[1,0,0] neg_lo:[1,0,0] neg_hi:[1,0,0]
	v_pk_fma_f32 v[152:153], v[152:153], 2.0, 1.0 op_sel_hi:[1,0,0] neg_lo:[1,0,0] neg_hi:[1,0,0]
	v_pk_add_f32 v[150:151], v[150:151], 1.0 op_sel_hi:[1,0]
	v_pk_add_f32 v[152:153], v[152:153], 1.0 op_sel_hi:[1,0]
	v_pk_mul_f32 v[128:129], v[128:129], v[150:151]
	v_pk_mul_f32 v[130:131], v[130:131], v[152:153]
	s_nop 0
	v_cvt_pk_bf16_f32 v128, v128, v129
	v_cvt_pk_bf16_f32 v129, v130, v131
	global_store_dwordx2 v141, v[128:129], s[78:79]
	s_waitcnt vmcnt(15)
; __device__ __forceinline__ float bflo(unsigned w) { return __uint_as_float(w << 16); }
; __device__ __forceinline__ float bfhi(unsigned w) { return __uint_as_float(w & 0xffff0000u); }
; __device__ __forceinline__ unsigned pk2(float lo, float hi) { return pg8::cvt_pk_bf16(lo, hi); }
; __device__ __forceinline__ float gelu_tanh(float y) { const float a = 0.7978845608028654f * (y + 0.044715f * y * y * y); const float e = __expf(2.0f * a); const float th = 1.0f - 2.0f * __builtin_amdgcn_rcpf(e + 1.0f); return 0.5f * y * (1.0f + th); }
;     __device__ __forceinline__ void operator()(const f32x4 (&acc)[2][2][4][2], const Unit& u, int wr, int wc, int fr, int fq) const {
;     ...
;             for (int m = 0; m < 4; ++m) { const int rowg = mh * 256 + ai * 128 + wr * 64 + m * 16 + fr, b = rowg >> 6, c = rowg & 63;
; #pragma unroll
;                 for (int bj = 0; bj < 2; ++bj)
; #pragma unroll
;                     for (int n = 0; n < 2; ++n) { const int colg = nh * 256 + bj * 128 + wc * 32 + n * 16 + 4 * fq, tau = colg >> 4, ch = g * 16 + (colg & 15);
;                         const size_t tok = (size_t)b * SEQ + 32 * c + tau;
;                         const u32x2 uw = *(const u32x2*)(z + tok * ZP + C_SU + ch); const f32x4 d4 = *(const f32x4*)(dsk + ch); const f32x4 a = acc[ai][bj][m][n];
;                         u32x2 o; o.x = pk2(gelu_tanh(a[0] + d4[0] * bflo(uw.x)), gelu_tanh(a[1] + d4[1] * bfhi(uw.x))); o.y = pk2(gelu_tanh(a[2] + d4[2] * bflo(uw.y)), gelu_tanh(a[3] + d4[3] * bfhi(uw.y)));
;                         *(u32x2*)(ysg + tok * 512 + ch) = o; } }
	v_lshlrev_b32_e32 v150, 16, v164
	v_and_b32_e32 v151, 0xffff0000, v164
	v_lshlrev_b32_e32 v152, 16, v165
	v_and_b32_e32 v153, 0xffff0000, v165
	v_or_b32_e32 v139, s20, v134
	v_pk_fma_f32 v[124:125], v[154:155], v[150:151], v[124:125]
	v_pk_fma_f32 v[126:127], v[156:157], v[152:153], v[126:127]
	v_or_b32_e32 v139, s5, v139
	v_lshl_add_u32 v141, v139, 10, v146
	v_mul_f32_e32 v150, 0x3d372713, v124
	v_mul_f32_e32 v151, 0x3d372713, v125
	v_mul_f32_e32 v152, 0x3d372713, v126
	v_mul_f32_e32 v153, 0x3d372713, v127
	v_mul_f32_e32 v150, v124, v150
	v_mul_f32_e32 v151, v125, v151
	v_mul_f32_e32 v152, v126, v152
	v_mul_f32_e32 v153, v127, v153
	v_fma_f32 v150, v124, v150, v124
	v_fma_f32 v151, v125, v151, v125
	v_fma_f32 v152, v126, v152, v126
	v_fma_f32 v153, v127, v153, v127
	v_mul_f32_e32 v150, 0x3f4c422a, v150
	v_mul_f32_e32 v151, 0x3f4c422a, v151
	v_mul_f32_e32 v152, 0x3f4c422a, v152
	v_mul_f32_e32 v153, 0x3f4c422a, v153
	v_add_f32_e32 v150, v150, v150
	v_add_f32_e32 v151, v151, v151
	v_add_f32_e32 v152, v152, v152
	v_add_f32_e32 v153, v153, v153
	v_mul_f32_e32 v150, 0x3fb8aa3b, v150
	v_mul_f32_e32 v151, 0x3fb8aa3b, v151
	v_mul_f32_e32 v152, 0x3fb8aa3b, v152
	v_mul_f32_e32 v153, 0x3fb8aa3b, v153
	v_exp_f32_e32 v150, v150
	v_exp_f32_e32 v151, v151
	v_exp_f32_e32 v152, v152
	v_exp_f32_e32 v153, v153
	v_add_f32_e32 v150, 1.0, v150
	v_add_f32_e32 v151, 1.0, v151
	v_add_f32_e32 v152, 1.0, v152
	v_add_f32_e32 v153, 1.0, v153
	v_rcp_f32_e32 v150, v150
	v_rcp_f32_e32 v151, v151
	v_rcp_f32_e32 v152, v152
	v_rcp_f32_e32 v153, v153
	v_pk_mul_f32 v[124:125], v[124:125], 0.5 op_sel_hi:[1,0]
	v_pk_mul_f32 v[126:127], v[126:127], 0.5 op_sel_hi:[1,0]
	v_pk_fma_f32 v[150:151], v[150:151], 2.0, 1.0 op_sel_hi:[1,0,0] neg_lo:[1,0,0] neg_hi:[1,0,0]
	v_pk_fma_f32 v[152:153], v[152:153], 2.0, 1.0 op_sel_hi:[1,0,0] neg_lo:[1,0,0] neg_hi:[1,0,0]
	v_pk_add_f32 v[150:151], v[150:151], 1.0 op_sel_hi:[1,0]
	v_pk_add_f32 v[152:153], v[152:153], 1.0 op_sel_hi:[1,0]
	v_pk_mul_f32 v[124:125], v[124:125], v[150:151]
	v_pk_mul_f32 v[126:127], v[126:127], v[152:153]
	s_nop 0
	v_cvt_pk_bf16_f32 v124, v124, v125
	v_cvt_pk_bf16_f32 v125, v126, v127
	global_store_dwordx2 v141, v[124:125], s[78:79]
	s_waitcnt vmcnt(15)
	v_lshlrev_b32_e32 v150, 16, v166
	v_and_b32_e32 v151, 0xffff0000, v166
	v_lshlrev_b32_e32 v152, 16, v167
	v_and_b32_e32 v153, 0xffff0000, v167
	v_or_b32_e32 v139, s20, v134
	v_pk_fma_f32 v[120:121], v[154:155], v[150:151], v[120:121]
	v_pk_fma_f32 v[122:123], v[156:157], v[152:153], v[122:123]
	v_or_b32_e32 v139, s4, v139
	v_lshl_add_u32 v141, v139, 10, v146
	v_mul_f32_e32 v150, 0x3d372713, v120
	v_mul_f32_e32 v151, 0x3d372713, v121
	v_mul_f32_e32 v152, 0x3d372713, v122
	v_mul_f32_e32 v153, 0x3d372713, v123
	v_mul_f32_e32 v150, v120, v150
	v_mul_f32_e32 v151, v121, v151
	v_mul_f32_e32 v152, v122, v152
	v_mul_f32_e32 v153, v123, v153
	v_fma_f32 v150, v120, v150, v120
	v_fma_f32 v151, v121, v151, v121
	v_fma_f32 v152, v122, v152, v122
	v_fma_f32 v153, v123, v153, v123
	v_mul_f32_e32 v150, 0x3f4c422a, v150
	v_mul_f32_e32 v151, 0x3f4c422a, v151
	v_mul_f32_e32 v152, 0x3f4c422a, v152
	v_mul_f32_e32 v153, 0x3f4c422a, v153
	v_add_f32_e32 v150, v150, v150
	v_add_f32_e32 v151, v151, v151
	v_add_f32_e32 v152, v152, v152
	v_add_f32_e32 v153, v153, v153
	v_mul_f32_e32 v150, 0x3fb8aa3b, v150
	v_mul_f32_e32 v151, 0x3fb8aa3b, v151
	v_mul_f32_e32 v152, 0x3fb8aa3b, v152
	v_mul_f32_e32 v153, 0x3fb8aa3b, v153
	v_exp_f32_e32 v150, v150
	v_exp_f32_e32 v151, v151
	v_exp_f32_e32 v152, v152
	v_exp_f32_e32 v153, v153
	v_add_f32_e32 v150, 1.0, v150
	v_add_f32_e32 v151, 1.0, v151
	v_add_f32_e32 v152, 1.0, v152
	v_add_f32_e32 v153, 1.0, v153
	v_rcp_f32_e32 v150, v150
	v_rcp_f32_e32 v151, v151
	v_rcp_f32_e32 v152, v152
	v_rcp_f32_e32 v153, v153
	v_pk_mul_f32 v[120:121], v[120:121], 0.5 op_sel_hi:[1,0]
	v_pk_mul_f32 v[122:123], v[122:123], 0.5 op_sel_hi:[1,0]
	v_pk_fma_f32 v[150:151], v[150:151], 2.0, 1.0 op_sel_hi:[1,0,0] neg_lo:[1,0,0] neg_hi:[1,0,0]
	v_pk_fma_f32 v[152:153], v[152:153], 2.0, 1.0 op_sel_hi:[1,0,0] neg_lo:[1,0,0] neg_hi:[1,0,0]
	v_pk_add_f32 v[150:151], v[150:151], 1.0 op_sel_hi:[1,0]
	v_pk_add_f32 v[152:153], v[152:153], 1.0 op_sel_hi:[1,0]
	v_pk_mul_f32 v[120:121], v[120:121], v[150:151]
	v_pk_mul_f32 v[122:123], v[122:123], v[152:153]
	s_nop 0
	v_cvt_pk_bf16_f32 v120, v120, v121
	v_cvt_pk_bf16_f32 v121, v122, v123
	global_store_dwordx2 v141, v[120:121], s[78:79]
	s_waitcnt vmcnt(15)
	v_lshlrev_b32_e32 v150, 16, v168
	v_and_b32_e32 v151, 0xffff0000, v168
	v_lshlrev_b32_e32 v152, 16, v169
	v_and_b32_e32 v153, 0xffff0000, v169
	v_or_b32_e32 v139, s20, v134
	v_pk_fma_f32 v[116:117], v[154:155], v[150:151], v[116:117]
	v_pk_fma_f32 v[118:119], v[156:157], v[152:153], v[118:119]
	v_or_b32_e32 v139, s6, v139
	v_lshl_add_u32 v141, v139, 10, v146
	v_mul_f32_e32 v150, 0x3d372713, v116
	v_mul_f32_e32 v151, 0x3d372713, v117
	v_mul_f32_e32 v152, 0x3d372713, v118
	v_mul_f32_e32 v153, 0x3d372713, v119
	v_mul_f32_e32 v150, v116, v150
	v_mul_f32_e32 v151, v117, v151
	v_mul_f32_e32 v152, v118, v152
	v_mul_f32_e32 v153, v119, v153
	v_fma_f32 v150, v116, v150, v116
	v_fma_f32 v151, v117, v151, v117
	v_fma_f32 v152, v118, v152, v118
	v_fma_f32 v153, v119, v153, v119
	v_mul_f32_e32 v150, 0x3f4c422a, v150
	v_mul_f32_e32 v151, 0x3f4c422a, v151
	v_mul_f32_e32 v152, 0x3f4c422a, v152
	v_mul_f32_e32 v153, 0x3f4c422a, v153
	v_add_f32_e32 v150, v150, v150
	v_add_f32_e32 v151, v151, v151
	v_add_f32_e32 v152, v152, v152
	v_add_f32_e32 v153, v153, v153
	v_mul_f32_e32 v150, 0x3fb8aa3b, v150
	v_mul_f32_e32 v151, 0x3fb8aa3b, v151
	v_mul_f32_e32 v152, 0x3fb8aa3b, v152
	v_mul_f32_e32 v153, 0x3fb8aa3b, v153
	v_exp_f32_e32 v150, v150
	v_exp_f32_e32 v151, v151
	v_exp_f32_e32 v152, v152
	v_exp_f32_e32 v153, v153
	v_add_f32_e32 v150, 1.0, v150
	v_add_f32_e32 v151, 1.0, v151
	v_add_f32_e32 v152, 1.0, v152
	v_add_f32_e32 v153, 1.0, v153
	v_rcp_f32_e32 v150, v150
	v_rcp_f32_e32 v151, v151
	v_rcp_f32_e32 v152, v152
	v_rcp_f32_e32 v153, v153
	v_pk_mul_f32 v[116:117], v[116:117], 0.5 op_sel_hi:[1,0]
	v_pk_mul_f32 v[118:119], v[118:119], 0.5 op_sel_hi:[1,0]
	v_pk_fma_f32 v[150:151], v[150:151], 2.0, 1.0 op_sel_hi:[1,0,0] neg_lo:[1,0,0] neg_hi:[1,0,0]
	v_pk_fma_f32 v[152:153], v[152:153], 2.0, 1.0 op_sel_hi:[1,0,0] neg_lo:[1,0,0] neg_hi:[1,0,0]
	v_pk_add_f32 v[150:151], v[150:151], 1.0 op_sel_hi:[1,0]
	v_pk_add_f32 v[152:153], v[152:153], 1.0 op_sel_hi:[1,0]
	v_pk_mul_f32 v[116:117], v[116:117], v[150:151]
	v_pk_mul_f32 v[118:119], v[118:119], v[152:153]
	s_nop 0
	v_cvt_pk_bf16_f32 v116, v116, v117
	v_cvt_pk_bf16_f32 v117, v118, v119
	global_store_dwordx2 v141, v[116:117], s[78:79]
	s_waitcnt vmcnt(15)
; __device__ __forceinline__ float bflo(unsigned w) { return __uint_as_float(w << 16); }
; __device__ __forceinline__ float bfhi(unsigned w) { return __uint_as_float(w & 0xffff0000u); }
; __device__ __forceinline__ unsigned pk2(float lo, float hi) { return pg8::cvt_pk_bf16(lo, hi); }
; __device__ __forceinline__ float gelu_tanh(float y) { const float a = 0.7978845608028654f * (y + 0.044715f * y * y * y); const float e = __expf(2.0f * a); const float th = 1.0f - 2.0f * __builtin_amdgcn_rcpf(e + 1.0f); return 0.5f * y * (1.0f + th); }
;     __device__ __forceinline__ void operator()(const f32x4 (&acc)[2][2][4][2], const Unit& u, int wr, int wc, int fr, int fq) const {
;     ...
;             for (int m = 0; m < 4; ++m) { const int rowg = mh * 256 + ai * 128 + wr * 64 + m * 16 + fr, b = rowg >> 6, c = rowg & 63;
; #pragma unroll
;                 for (int bj = 0; bj < 2; ++bj)
; #pragma unroll
;                     for (int n = 0; n < 2; ++n) { const int colg = nh * 256 + bj * 128 + wc * 32 + n * 16 + 4 * fq, tau = colg >> 4, ch = g * 16 + (colg & 15);
;                         const size_t tok = (size_t)b * SEQ + 32 * c + tau;
;                         const u32x2 uw = *(const u32x2*)(z + tok * ZP + C_SU + ch); const f32x4 d4 = *(const f32x4*)(dsk + ch); const f32x4 a = acc[ai][bj][m][n];
;                         u32x2 o; o.x = pk2(gelu_tanh(a[0] + d4[0] * bflo(uw.x)), gelu_tanh(a[1] + d4[1] * bfhi(uw.x))); o.y = pk2(gelu_tanh(a[2] + d4[2] * bflo(uw.y)), gelu_tanh(a[3] + d4[3] * bfhi(uw.y)));
;                         *(u32x2*)(ysg + tok * 512 + ch) = o; } }
	v_lshlrev_b32_e32 v150, 16, v170
	v_and_b32_e32 v151, 0xffff0000, v170
	v_lshlrev_b32_e32 v152, 16, v171
	v_and_b32_e32 v153, 0xffff0000, v171
	v_or_b32_e32 v139, s20, v136
	v_pk_fma_f32 v[112:113], v[154:155], v[150:151], v[112:113]
	v_pk_fma_f32 v[114:115], v[156:157], v[152:153], v[114:115]
	v_or_b32_e32 v139, s7, v139
	v_lshl_add_u32 v141, v139, 10, v146
	v_mul_f32_e32 v150, 0x3d372713, v112
	v_mul_f32_e32 v151, 0x3d372713, v113
	v_mul_f32_e32 v152, 0x3d372713, v114
	v_mul_f32_e32 v153, 0x3d372713, v115
	v_mul_f32_e32 v150, v112, v150
	v_mul_f32_e32 v151, v113, v151
	v_mul_f32_e32 v152, v114, v152
	v_mul_f32_e32 v153, v115, v153
	v_fma_f32 v150, v112, v150, v112
	v_fma_f32 v151, v113, v151, v113
	v_fma_f32 v152, v114, v152, v114
	v_fma_f32 v153, v115, v153, v115
	v_mul_f32_e32 v150, 0x3f4c422a, v150
	v_mul_f32_e32 v151, 0x3f4c422a, v151
	v_mul_f32_e32 v152, 0x3f4c422a, v152
	v_mul_f32_e32 v153, 0x3f4c422a, v153
	v_add_f32_e32 v150, v150, v150
	v_add_f32_e32 v151, v151, v151
	v_add_f32_e32 v152, v152, v152
	v_add_f32_e32 v153, v153, v153
	v_mul_f32_e32 v150, 0x3fb8aa3b, v150
	v_mul_f32_e32 v151, 0x3fb8aa3b, v151
	v_mul_f32_e32 v152, 0x3fb8aa3b, v152
	v_mul_f32_e32 v153, 0x3fb8aa3b, v153
	v_exp_f32_e32 v150, v150
	v_exp_f32_e32 v151, v151
	v_exp_f32_e32 v152, v152
	v_exp_f32_e32 v153, v153
	v_add_f32_e32 v150, 1.0, v150
	v_add_f32_e32 v151, 1.0, v151
	v_add_f32_e32 v152, 1.0, v152
	v_add_f32_e32 v153, 1.0, v153
	v_rcp_f32_e32 v150, v150
	v_rcp_f32_e32 v151, v151
	v_rcp_f32_e32 v152, v152
	v_rcp_f32_e32 v153, v153
	v_pk_mul_f32 v[112:113], v[112:113], 0.5 op_sel_hi:[1,0]
	v_pk_mul_f32 v[114:115], v[114:115], 0.5 op_sel_hi:[1,0]
	v_pk_fma_f32 v[150:151], v[150:151], 2.0, 1.0 op_sel_hi:[1,0,0] neg_lo:[1,0,0] neg_hi:[1,0,0]
	v_pk_fma_f32 v[152:153], v[152:153], 2.0, 1.0 op_sel_hi:[1,0,0] neg_lo:[1,0,0] neg_hi:[1,0,0]
	v_pk_add_f32 v[150:151], v[150:151], 1.0 op_sel_hi:[1,0]
	v_pk_add_f32 v[152:153], v[152:153], 1.0 op_sel_hi:[1,0]
	v_pk_mul_f32 v[112:113], v[112:113], v[150:151]
	v_pk_mul_f32 v[114:115], v[114:115], v[152:153]
	s_nop 0
	v_cvt_pk_bf16_f32 v112, v112, v113
	v_cvt_pk_bf16_f32 v113, v114, v115
	global_store_dwordx2 v141, v[112:113], s[78:79]
	s_waitcnt vmcnt(15)
	v_lshlrev_b32_e32 v150, 16, v172
	v_and_b32_e32 v151, 0xffff0000, v172
	v_lshlrev_b32_e32 v152, 16, v173
	v_and_b32_e32 v153, 0xffff0000, v173
	v_or_b32_e32 v139, s20, v136
	v_pk_fma_f32 v[108:109], v[154:155], v[150:151], v[108:109]
	v_pk_fma_f32 v[110:111], v[156:157], v[152:153], v[110:111]
	v_or_b32_e32 v139, s5, v139
	v_lshl_add_u32 v141, v139, 10, v146
	v_mul_f32_e32 v150, 0x3d372713, v108
	v_mul_f32_e32 v151, 0x3d372713, v109
	v_mul_f32_e32 v152, 0x3d372713, v110
	v_mul_f32_e32 v153, 0x3d372713, v111
	v_mul_f32_e32 v150, v108, v150
	v_mul_f32_e32 v151, v109, v151
	v_mul_f32_e32 v152, v110, v152
	v_mul_f32_e32 v153, v111, v153
	v_fma_f32 v150, v108, v150, v108
	v_fma_f32 v151, v109, v151, v109
	v_fma_f32 v152, v110, v152, v110
	v_fma_f32 v153, v111, v153, v111
	v_mul_f32_e32 v150, 0x3f4c422a, v150
	v_mul_f32_e32 v151, 0x3f4c422a, v151
	v_mul_f32_e32 v152, 0x3f4c422a, v152
	v_mul_f32_e32 v153, 0x3f4c422a, v153
	v_add_f32_e32 v150, v150, v150
	v_add_f32_e32 v151, v151, v151
	v_add_f32_e32 v152, v152, v152
	v_add_f32_e32 v153, v153, v153
	v_mul_f32_e32 v150, 0x3fb8aa3b, v150
	v_mul_f32_e32 v151, 0x3fb8aa3b, v151
	v_mul_f32_e32 v152, 0x3fb8aa3b, v152
	v_mul_f32_e32 v153, 0x3fb8aa3b, v153
	v_exp_f32_e32 v150, v150
	v_exp_f32_e32 v151, v151
	v_exp_f32_e32 v152, v152
	v_exp_f32_e32 v153, v153
	v_add_f32_e32 v150, 1.0, v150
	v_add_f32_e32 v151, 1.0, v151
	v_add_f32_e32 v152, 1.0, v152
	v_add_f32_e32 v153, 1.0, v153
	v_rcp_f32_e32 v150, v150
	v_rcp_f32_e32 v151, v151
	v_rcp_f32_e32 v152, v152
	v_rcp_f32_e32 v153, v153
	v_pk_mul_f32 v[108:109], v[108:109], 0.5 op_sel_hi:[1,0]
	v_pk_mul_f32 v[110:111], v[110:111], 0.5 op_sel_hi:[1,0]
	v_pk_fma_f32 v[150:151], v[150:151], 2.0, 1.0 op_sel_hi:[1,0,0] neg_lo:[1,0,0] neg_hi:[1,0,0]
	v_pk_fma_f32 v[152:153], v[152:153], 2.0, 1.0 op_sel_hi:[1,0,0] neg_lo:[1,0,0] neg_hi:[1,0,0]
	v_pk_add_f32 v[150:151], v[150:151], 1.0 op_sel_hi:[1,0]
	v_pk_add_f32 v[152:153], v[152:153], 1.0 op_sel_hi:[1,0]
	v_pk_mul_f32 v[108:109], v[108:109], v[150:151]
	v_pk_mul_f32 v[110:111], v[110:111], v[152:153]
	s_nop 0
	v_cvt_pk_bf16_f32 v108, v108, v109
	v_cvt_pk_bf16_f32 v109, v110, v111
	global_store_dwordx2 v141, v[108:109], s[78:79]
	s_waitcnt vmcnt(15)
	v_lshlrev_b32_e32 v150, 16, v186
	v_and_b32_e32 v151, 0xffff0000, v186
	v_lshlrev_b32_e32 v152, 16, v187
	v_and_b32_e32 v153, 0xffff0000, v187
	v_or_b32_e32 v139, s20, v136
	v_pk_fma_f32 v[104:105], v[154:155], v[150:151], v[104:105]
	v_pk_fma_f32 v[106:107], v[156:157], v[152:153], v[106:107]
	v_or_b32_e32 v139, s4, v139
	v_lshl_add_u32 v141, v139, 10, v146
	v_mul_f32_e32 v150, 0x3d372713, v104
	v_mul_f32_e32 v151, 0x3d372713, v105
	v_mul_f32_e32 v152, 0x3d372713, v106
	v_mul_f32_e32 v153, 0x3d372713, v107
	v_mul_f32_e32 v150, v104, v150
	v_mul_f32_e32 v151, v105, v151
	v_mul_f32_e32 v152, v106, v152
	v_mul_f32_e32 v153, v107, v153
	v_fma_f32 v150, v104, v150, v104
	v_fma_f32 v151, v105, v151, v105
	v_fma_f32 v152, v106, v152, v106
	v_fma_f32 v153, v107, v153, v107
	v_mul_f32_e32 v150, 0x3f4c422a, v150
	v_mul_f32_e32 v151, 0x3f4c422a, v151
	v_mul_f32_e32 v152, 0x3f4c422a, v152
	v_mul_f32_e32 v153, 0x3f4c422a, v153
	v_add_f32_e32 v150, v150, v150
	v_add_f32_e32 v151, v151, v151
	v_add_f32_e32 v152, v152, v152
	v_add_f32_e32 v153, v153, v153
	v_mul_f32_e32 v150, 0x3fb8aa3b, v150
	v_mul_f32_e32 v151, 0x3fb8aa3b, v151
	v_mul_f32_e32 v152, 0x3fb8aa3b, v152
	v_mul_f32_e32 v153, 0x3fb8aa3b, v153
	v_exp_f32_e32 v150, v150
	v_exp_f32_e32 v151, v151
	v_exp_f32_e32 v152, v152
	v_exp_f32_e32 v153, v153
	v_add_f32_e32 v150, 1.0, v150
	v_add_f32_e32 v151, 1.0, v151
	v_add_f32_e32 v152, 1.0, v152
	v_add_f32_e32 v153, 1.0, v153
	v_rcp_f32_e32 v150, v150
	v_rcp_f32_e32 v151, v151
	v_rcp_f32_e32 v152, v152
	v_rcp_f32_e32 v153, v153
	v_pk_mul_f32 v[104:105], v[104:105], 0.5 op_sel_hi:[1,0]
	v_pk_mul_f32 v[106:107], v[106:107], 0.5 op_sel_hi:[1,0]
	v_pk_fma_f32 v[150:151], v[150:151], 2.0, 1.0 op_sel_hi:[1,0,0] neg_lo:[1,0,0] neg_hi:[1,0,0]
	v_pk_fma_f32 v[152:153], v[152:153], 2.0, 1.0 op_sel_hi:[1,0,0] neg_lo:[1,0,0] neg_hi:[1,0,0]
	v_pk_add_f32 v[150:151], v[150:151], 1.0 op_sel_hi:[1,0]
	v_pk_add_f32 v[152:153], v[152:153], 1.0 op_sel_hi:[1,0]
	v_pk_mul_f32 v[104:105], v[104:105], v[150:151]
	v_pk_mul_f32 v[106:107], v[106:107], v[152:153]
	s_nop 0
	v_cvt_pk_bf16_f32 v104, v104, v105
	v_cvt_pk_bf16_f32 v105, v106, v107
	global_store_dwordx2 v141, v[104:105], s[78:79]
	s_waitcnt vmcnt(15)
; __device__ __forceinline__ float bflo(unsigned w) { return __uint_as_float(w << 16); }
; __device__ __forceinline__ float bfhi(unsigned w) { return __uint_as_float(w & 0xffff0000u); }
; __device__ __forceinline__ unsigned pk2(float lo, float hi) { return pg8::cvt_pk_bf16(lo, hi); }
; __device__ __forceinline__ float gelu_tanh(float y) { const float a = 0.7978845608028654f * (y + 0.044715f * y * y * y); const float e = __expf(2.0f * a); const float th = 1.0f - 2.0f * __builtin_amdgcn_rcpf(e + 1.0f); return 0.5f * y * (1.0f + th); }
;     __device__ __forceinline__ void operator()(const f32x4 (&acc)[2][2][4][2], const Unit& u, int wr, int wc, int fr, int fq) const {
;     ...
;             for (int m = 0; m < 4; ++m) { const int rowg = mh * 256 + ai * 128 + wr * 64 + m * 16 + fr, b = rowg >> 6, c = rowg & 63;
; #pragma unroll
;                 for (int bj = 0; bj < 2; ++bj)
; #pragma unroll
;                     for (int n = 0; n < 2; ++n) { const int colg = nh * 256 + bj * 128 + wc * 32 + n * 16 + 4 * fq, tau = colg >> 4, ch = g * 16 + (colg & 15);
;                         const size_t tok = (size_t)b * SEQ + 32 * c + tau;
;                         const u32x2 uw = *(const u32x2*)(z + tok * ZP + C_SU + ch); const f32x4 d4 = *(const f32x4*)(dsk + ch); const f32x4 a = acc[ai][bj][m][n];
;                         u32x2 o; o.x = pk2(gelu_tanh(a[0] + d4[0] * bflo(uw.x)), gelu_tanh(a[1] + d4[1] * bfhi(uw.x))); o.y = pk2(gelu_tanh(a[2] + d4[2] * bflo(uw.y)), gelu_tanh(a[3] + d4[3] * bfhi(uw.y)));
;                         *(u32x2*)(ysg + tok * 512 + ch) = o; } }
	v_lshlrev_b32_e32 v150, 16, v188
	v_and_b32_e32 v151, 0xffff0000, v188
	v_lshlrev_b32_e32 v152, 16, v189
	v_and_b32_e32 v153, 0xffff0000, v189
	v_or_b32_e32 v139, s20, v136
	v_pk_fma_f32 v[100:101], v[154:155], v[150:151], v[100:101]
	v_pk_fma_f32 v[102:103], v[156:157], v[152:153], v[102:103]
	v_or_b32_e32 v139, s6, v139
	v_lshl_add_u32 v141, v139, 10, v146
	v_mul_f32_e32 v150, 0x3d372713, v100
	v_mul_f32_e32 v151, 0x3d372713, v101
	v_mul_f32_e32 v152, 0x3d372713, v102
	v_mul_f32_e32 v153, 0x3d372713, v103
	v_mul_f32_e32 v150, v100, v150
	v_mul_f32_e32 v151, v101, v151
	v_mul_f32_e32 v152, v102, v152
	v_mul_f32_e32 v153, v103, v153
	v_fma_f32 v150, v100, v150, v100
	v_fma_f32 v151, v101, v151, v101
	v_fma_f32 v152, v102, v152, v102
	v_fma_f32 v153, v103, v153, v103
	v_mul_f32_e32 v150, 0x3f4c422a, v150
	v_mul_f32_e32 v151, 0x3f4c422a, v151
	v_mul_f32_e32 v152, 0x3f4c422a, v152
	v_mul_f32_e32 v153, 0x3f4c422a, v153
	v_add_f32_e32 v150, v150, v150
	v_add_f32_e32 v151, v151, v151
	v_add_f32_e32 v152, v152, v152
	v_add_f32_e32 v153, v153, v153
	v_mul_f32_e32 v150, 0x3fb8aa3b, v150
	v_mul_f32_e32 v151, 0x3fb8aa3b, v151
	v_mul_f32_e32 v152, 0x3fb8aa3b, v152
	v_mul_f32_e32 v153, 0x3fb8aa3b, v153
	v_exp_f32_e32 v150, v150
	v_exp_f32_e32 v151, v151
	v_exp_f32_e32 v152, v152
	v_exp_f32_e32 v153, v153
	v_add_f32_e32 v150, 1.0, v150
	v_add_f32_e32 v151, 1.0, v151
	v_add_f32_e32 v152, 1.0, v152
	v_add_f32_e32 v153, 1.0, v153
	v_rcp_f32_e32 v150, v150
	v_rcp_f32_e32 v151, v151
	v_rcp_f32_e32 v152, v152
	v_rcp_f32_e32 v153, v153
	v_pk_mul_f32 v[100:101], v[100:101], 0.5 op_sel_hi:[1,0]
	v_pk_mul_f32 v[102:103], v[102:103], 0.5 op_sel_hi:[1,0]
	v_pk_fma_f32 v[150:151], v[150:151], 2.0, 1.0 op_sel_hi:[1,0,0] neg_lo:[1,0,0] neg_hi:[1,0,0]
	v_pk_fma_f32 v[152:153], v[152:153], 2.0, 1.0 op_sel_hi:[1,0,0] neg_lo:[1,0,0] neg_hi:[1,0,0]
	v_pk_add_f32 v[150:151], v[150:151], 1.0 op_sel_hi:[1,0]
	v_pk_add_f32 v[152:153], v[152:153], 1.0 op_sel_hi:[1,0]
	v_pk_mul_f32 v[100:101], v[100:101], v[150:151]
	v_pk_mul_f32 v[102:103], v[102:103], v[152:153]
	s_nop 0
	v_cvt_pk_bf16_f32 v100, v100, v101
	v_cvt_pk_bf16_f32 v101, v102, v103
	global_store_dwordx2 v141, v[100:101], s[78:79]
	v_or_b32_e32 v128, s22, v134
	v_or_b32_e32 v128, s7, v128
	v_mad_u32_u24 v128, v128, s88, v147
	global_load_dwordx2 v[128:129], v128, s[76:77]
	v_or_b32_e32 v130, s22, v134
	v_or_b32_e32 v130, s5, v130
	v_mad_u32_u24 v130, v130, s88, v147
	global_load_dwordx2 v[130:131], v130, s[76:77]
	v_or_b32_e32 v124, s22, v134
	v_or_b32_e32 v124, s4, v124
	v_mad_u32_u24 v124, v124, s88, v147
	global_load_dwordx2 v[124:125], v124, s[76:77]
	v_or_b32_e32 v126, s22, v134
	v_or_b32_e32 v126, s6, v126
	v_mad_u32_u24 v126, v126, s88, v147
	global_load_dwordx2 v[126:127], v126, s[76:77]
	v_or_b32_e32 v120, s22, v136
	v_or_b32_e32 v120, s7, v120
	v_mad_u32_u24 v120, v120, s88, v147
	global_load_dwordx2 v[120:121], v120, s[76:77]
	v_or_b32_e32 v122, s22, v136
	v_or_b32_e32 v122, s5, v122
	v_mad_u32_u24 v122, v122, s88, v147
	global_load_dwordx2 v[122:123], v122, s[76:77]
	v_or_b32_e32 v116, s22, v136
	v_or_b32_e32 v116, s4, v116
	v_mad_u32_u24 v116, v116, s88, v147
	global_load_dwordx2 v[116:117], v116, s[76:77]
	v_or_b32_e32 v118, s22, v136
	v_or_b32_e32 v118, s6, v118
	v_mad_u32_u24 v118, v118, s88, v147
	global_load_dwordx2 v[118:119], v118, s[76:77]
	v_or_b32_e32 v112, s22, v138
	v_or_b32_e32 v112, s7, v112
	v_mad_u32_u24 v112, v112, s88, v147
	global_load_dwordx2 v[112:113], v112, s[76:77]
	v_or_b32_e32 v114, s22, v138
	v_or_b32_e32 v114, s5, v114
	v_mad_u32_u24 v114, v114, s88, v147
	global_load_dwordx2 v[114:115], v114, s[76:77]
	v_or_b32_e32 v108, s22, v138
	v_or_b32_e32 v108, s4, v108
	v_mad_u32_u24 v108, v108, s88, v147
	global_load_dwordx2 v[108:109], v108, s[76:77]
	v_or_b32_e32 v110, s22, v138
	v_or_b32_e32 v110, s6, v110
	v_mad_u32_u24 v110, v110, s88, v147
	global_load_dwordx2 v[110:111], v110, s[76:77]
	v_or_b32_e32 v104, s22, v140
	v_or_b32_e32 v104, s7, v104
	v_mad_u32_u24 v104, v104, s88, v147
	global_load_dwordx2 v[104:105], v104, s[76:77]
	v_or_b32_e32 v106, s22, v140
	v_or_b32_e32 v106, s5, v106
	v_mad_u32_u24 v106, v106, s88, v147
	global_load_dwordx2 v[106:107], v106, s[76:77]
	v_or_b32_e32 v100, s22, v140
	v_or_b32_e32 v100, s4, v100
	v_mad_u32_u24 v100, v100, s88, v147
	global_load_dwordx2 v[100:101], v100, s[76:77]
	v_or_b32_e32 v102, s22, v140
	v_or_b32_e32 v102, s6, v102
	v_mad_u32_u24 v102, v102, s88, v147
	global_load_dwordx2 v[102:103], v102, s[76:77]
	s_waitcnt vmcnt(31)
	v_lshlrev_b32_e32 v150, 16, v190
	v_and_b32_e32 v151, 0xffff0000, v190
	v_lshlrev_b32_e32 v152, 16, v191
	v_and_b32_e32 v153, 0xffff0000, v191
	v_or_b32_e32 v139, s20, v138
	v_pk_fma_f32 v[96:97], v[154:155], v[150:151], v[96:97]
	v_pk_fma_f32 v[98:99], v[156:157], v[152:153], v[98:99]
	v_or_b32_e32 v139, s7, v139
	v_lshl_add_u32 v141, v139, 10, v146
	v_mul_f32_e32 v150, 0x3d372713, v96
	v_mul_f32_e32 v151, 0x3d372713, v97
	v_mul_f32_e32 v152, 0x3d372713, v98
	v_mul_f32_e32 v153, 0x3d372713, v99
	v_mul_f32_e32 v150, v96, v150
	v_mul_f32_e32 v151, v97, v151
	v_mul_f32_e32 v152, v98, v152
	v_mul_f32_e32 v153, v99, v153
	v_fma_f32 v150, v96, v150, v96
	v_fma_f32 v151, v97, v151, v97
	v_fma_f32 v152, v98, v152, v98
	v_fma_f32 v153, v99, v153, v99
	v_mul_f32_e32 v150, 0x3f4c422a, v150
	v_mul_f32_e32 v151, 0x3f4c422a, v151
	v_mul_f32_e32 v152, 0x3f4c422a, v152
	v_mul_f32_e32 v153, 0x3f4c422a, v153
	v_add_f32_e32 v150, v150, v150
	v_add_f32_e32 v151, v151, v151
	v_add_f32_e32 v152, v152, v152
	v_add_f32_e32 v153, v153, v153
	v_mul_f32_e32 v150, 0x3fb8aa3b, v150
	v_mul_f32_e32 v151, 0x3fb8aa3b, v151
	v_mul_f32_e32 v152, 0x3fb8aa3b, v152
	v_mul_f32_e32 v153, 0x3fb8aa3b, v153
	v_exp_f32_e32 v150, v150
	v_exp_f32_e32 v151, v151
	v_exp_f32_e32 v152, v152
	v_exp_f32_e32 v153, v153
	v_add_f32_e32 v150, 1.0, v150
	v_add_f32_e32 v151, 1.0, v151
	v_add_f32_e32 v152, 1.0, v152
	v_add_f32_e32 v153, 1.0, v153
	v_rcp_f32_e32 v150, v150
	v_rcp_f32_e32 v151, v151
	v_rcp_f32_e32 v152, v152
	v_rcp_f32_e32 v153, v153
	v_pk_mul_f32 v[96:97], v[96:97], 0.5 op_sel_hi:[1,0]
	v_pk_mul_f32 v[98:99], v[98:99], 0.5 op_sel_hi:[1,0]
	v_pk_fma_f32 v[150:151], v[150:151], 2.0, 1.0 op_sel_hi:[1,0,0] neg_lo:[1,0,0] neg_hi:[1,0,0]
	v_pk_fma_f32 v[152:153], v[152:153], 2.0, 1.0 op_sel_hi:[1,0,0] neg_lo:[1,0,0] neg_hi:[1,0,0]
	v_pk_add_f32 v[150:151], v[150:151], 1.0 op_sel_hi:[1,0]
	v_pk_add_f32 v[152:153], v[152:153], 1.0 op_sel_hi:[1,0]
	v_pk_mul_f32 v[96:97], v[96:97], v[150:151]
	v_pk_mul_f32 v[98:99], v[98:99], v[152:153]
	s_nop 0
	v_cvt_pk_bf16_f32 v96, v96, v97
	v_cvt_pk_bf16_f32 v97, v98, v99
	global_store_dwordx2 v141, v[96:97], s[78:79]
	s_waitcnt vmcnt(31)
; __device__ __forceinline__ float bflo(unsigned w) { return __uint_as_float(w << 16); }
; __device__ __forceinline__ float bfhi(unsigned w) { return __uint_as_float(w & 0xffff0000u); }
; __device__ __forceinline__ unsigned pk2(float lo, float hi) { return pg8::cvt_pk_bf16(lo, hi); }
; __device__ __forceinline__ float gelu_tanh(float y) { const float a = 0.7978845608028654f * (y + 0.044715f * y * y * y); const float e = __expf(2.0f * a); const float th = 1.0f - 2.0f * __builtin_amdgcn_rcpf(e + 1.0f); return 0.5f * y * (1.0f + th); }
;     __device__ __forceinline__ void operator()(const f32x4 (&acc)[2][2][4][2], const Unit& u, int wr, int wc, int fr, int fq) const {
;     ...
;             for (int m = 0; m < 4; ++m) { const int rowg = mh * 256 + ai * 128 + wr * 64 + m * 16 + fr, b = rowg >> 6, c = rowg & 63;
; #pragma unroll
;                 for (int bj = 0; bj < 2; ++bj)
; #pragma unroll
;                     for (int n = 0; n < 2; ++n) { const int colg = nh * 256 + bj * 128 + wc * 32 + n * 16 + 4 * fq, tau = colg >> 4, ch = g * 16 + (colg & 15);
;                         const size_t tok = (size_t)b * SEQ + 32 * c + tau;
;                         const u32x2 uw = *(const u32x2*)(z + tok * ZP + C_SU + ch); const f32x4 d4 = *(const f32x4*)(dsk + ch); const f32x4 a = acc[ai][bj][m][n];
;                         u32x2 o; o.x = pk2(gelu_tanh(a[0] + d4[0] * bflo(uw.x)), gelu_tanh(a[1] + d4[1] * bfhi(uw.x))); o.y = pk2(gelu_tanh(a[2] + d4[2] * bflo(uw.y)), gelu_tanh(a[3] + d4[3] * bfhi(uw.y)));
;                         *(u32x2*)(ysg + tok * 512 + ch) = o; } }
	v_lshlrev_b32_e32 v150, 16, v192
	v_and_b32_e32 v151, 0xffff0000, v192
	v_lshlrev_b32_e32 v152, 16, v193
	v_and_b32_e32 v153, 0xffff0000, v193
	v_or_b32_e32 v139, s20, v138
	v_pk_fma_f32 v[92:93], v[154:155], v[150:151], v[92:93]
	v_pk_fma_f32 v[94:95], v[156:157], v[152:153], v[94:95]
	v_or_b32_e32 v139, s5, v139
	v_lshl_add_u32 v141, v139, 10, v146
	v_mul_f32_e32 v150, 0x3d372713, v92
	v_mul_f32_e32 v151, 0x3d372713, v93
	v_mul_f32_e32 v152, 0x3d372713, v94
	v_mul_f32_e32 v153, 0x3d372713, v95
	v_mul_f32_e32 v150, v92, v150
	v_mul_f32_e32 v151, v93, v151
	v_mul_f32_e32 v152, v94, v152
	v_mul_f32_e32 v153, v95, v153
	v_fma_f32 v150, v92, v150, v92
	v_fma_f32 v151, v93, v151, v93
	v_fma_f32 v152, v94, v152, v94
	v_fma_f32 v153, v95, v153, v95
	v_mul_f32_e32 v150, 0x3f4c422a, v150
	v_mul_f32_e32 v151, 0x3f4c422a, v151
	v_mul_f32_e32 v152, 0x3f4c422a, v152
	v_mul_f32_e32 v153, 0x3f4c422a, v153
	v_add_f32_e32 v150, v150, v150
	v_add_f32_e32 v151, v151, v151
	v_add_f32_e32 v152, v152, v152
	v_add_f32_e32 v153, v153, v153
	v_mul_f32_e32 v150, 0x3fb8aa3b, v150
	v_mul_f32_e32 v151, 0x3fb8aa3b, v151
	v_mul_f32_e32 v152, 0x3fb8aa3b, v152
	v_mul_f32_e32 v153, 0x3fb8aa3b, v153
	v_exp_f32_e32 v150, v150
	v_exp_f32_e32 v151, v151
	v_exp_f32_e32 v152, v152
	v_exp_f32_e32 v153, v153
	v_add_f32_e32 v150, 1.0, v150
	v_add_f32_e32 v151, 1.0, v151
	v_add_f32_e32 v152, 1.0, v152
	v_add_f32_e32 v153, 1.0, v153
	v_rcp_f32_e32 v150, v150
	v_rcp_f32_e32 v151, v151
	v_rcp_f32_e32 v152, v152
	v_rcp_f32_e32 v153, v153
	v_pk_mul_f32 v[92:93], v[92:93], 0.5 op_sel_hi:[1,0]
	v_pk_mul_f32 v[94:95], v[94:95], 0.5 op_sel_hi:[1,0]
	v_pk_fma_f32 v[150:151], v[150:151], 2.0, 1.0 op_sel_hi:[1,0,0] neg_lo:[1,0,0] neg_hi:[1,0,0]
	v_pk_fma_f32 v[152:153], v[152:153], 2.0, 1.0 op_sel_hi:[1,0,0] neg_lo:[1,0,0] neg_hi:[1,0,0]
	v_pk_add_f32 v[150:151], v[150:151], 1.0 op_sel_hi:[1,0]
	v_pk_add_f32 v[152:153], v[152:153], 1.0 op_sel_hi:[1,0]
	v_pk_mul_f32 v[92:93], v[92:93], v[150:151]
	v_pk_mul_f32 v[94:95], v[94:95], v[152:153]
	s_nop 0
	v_cvt_pk_bf16_f32 v92, v92, v93
	v_cvt_pk_bf16_f32 v93, v94, v95
	global_store_dwordx2 v141, v[92:93], s[78:79]
	s_waitcnt vmcnt(31)
	v_lshlrev_b32_e32 v150, 16, v194
	v_and_b32_e32 v151, 0xffff0000, v194
	v_lshlrev_b32_e32 v152, 16, v195
	v_and_b32_e32 v153, 0xffff0000, v195
	v_or_b32_e32 v139, s20, v138
	v_pk_fma_f32 v[88:89], v[154:155], v[150:151], v[88:89]
	v_pk_fma_f32 v[90:91], v[156:157], v[152:153], v[90:91]
	v_or_b32_e32 v139, s4, v139
	v_lshl_add_u32 v141, v139, 10, v146
	v_mul_f32_e32 v150, 0x3d372713, v88
	v_mul_f32_e32 v151, 0x3d372713, v89
	v_mul_f32_e32 v152, 0x3d372713, v90
	v_mul_f32_e32 v153, 0x3d372713, v91
	v_mul_f32_e32 v150, v88, v150
	v_mul_f32_e32 v151, v89, v151
	v_mul_f32_e32 v152, v90, v152
	v_mul_f32_e32 v153, v91, v153
	v_fma_f32 v150, v88, v150, v88
	v_fma_f32 v151, v89, v151, v89
	v_fma_f32 v152, v90, v152, v90
	v_fma_f32 v153, v91, v153, v91
	v_mul_f32_e32 v150, 0x3f4c422a, v150
	v_mul_f32_e32 v151, 0x3f4c422a, v151
	v_mul_f32_e32 v152, 0x3f4c422a, v152
	v_mul_f32_e32 v153, 0x3f4c422a, v153
	v_add_f32_e32 v150, v150, v150
	v_add_f32_e32 v151, v151, v151
	v_add_f32_e32 v152, v152, v152
	v_add_f32_e32 v153, v153, v153
	v_mul_f32_e32 v150, 0x3fb8aa3b, v150
	v_mul_f32_e32 v151, 0x3fb8aa3b, v151
	v_mul_f32_e32 v152, 0x3fb8aa3b, v152
	v_mul_f32_e32 v153, 0x3fb8aa3b, v153
	v_exp_f32_e32 v150, v150
	v_exp_f32_e32 v151, v151
	v_exp_f32_e32 v152, v152
	v_exp_f32_e32 v153, v153
	v_add_f32_e32 v150, 1.0, v150
	v_add_f32_e32 v151, 1.0, v151
	v_add_f32_e32 v152, 1.0, v152
	v_add_f32_e32 v153, 1.0, v153
	v_rcp_f32_e32 v150, v150
	v_rcp_f32_e32 v151, v151
	v_rcp_f32_e32 v152, v152
	v_rcp_f32_e32 v153, v153
	v_pk_mul_f32 v[88:89], v[88:89], 0.5 op_sel_hi:[1,0]
	v_pk_mul_f32 v[90:91], v[90:91], 0.5 op_sel_hi:[1,0]
	v_pk_fma_f32 v[150:151], v[150:151], 2.0, 1.0 op_sel_hi:[1,0,0] neg_lo:[1,0,0] neg_hi:[1,0,0]
	v_pk_fma_f32 v[152:153], v[152:153], 2.0, 1.0 op_sel_hi:[1,0,0] neg_lo:[1,0,0] neg_hi:[1,0,0]
	v_pk_add_f32 v[150:151], v[150:151], 1.0 op_sel_hi:[1,0]
	v_pk_add_f32 v[152:153], v[152:153], 1.0 op_sel_hi:[1,0]
	v_pk_mul_f32 v[88:89], v[88:89], v[150:151]
	v_pk_mul_f32 v[90:91], v[90:91], v[152:153]
	s_nop 0
	v_cvt_pk_bf16_f32 v88, v88, v89
	v_cvt_pk_bf16_f32 v89, v90, v91
	global_store_dwordx2 v141, v[88:89], s[78:79]
	s_waitcnt vmcnt(31)
	v_lshlrev_b32_e32 v150, 16, v196
	v_and_b32_e32 v151, 0xffff0000, v196
	v_lshlrev_b32_e32 v152, 16, v197
	v_and_b32_e32 v153, 0xffff0000, v197
	v_or_b32_e32 v139, s20, v138
	v_pk_fma_f32 v[84:85], v[154:155], v[150:151], v[84:85]
	v_pk_fma_f32 v[86:87], v[156:157], v[152:153], v[86:87]
	v_or_b32_e32 v139, s6, v139
	v_lshl_add_u32 v141, v139, 10, v146
	v_mul_f32_e32 v150, 0x3d372713, v84
	v_mul_f32_e32 v151, 0x3d372713, v85
	v_mul_f32_e32 v152, 0x3d372713, v86
	v_mul_f32_e32 v153, 0x3d372713, v87
	v_mul_f32_e32 v150, v84, v150
	v_mul_f32_e32 v151, v85, v151
	v_mul_f32_e32 v152, v86, v152
	v_mul_f32_e32 v153, v87, v153
	v_fma_f32 v150, v84, v150, v84
	v_fma_f32 v151, v85, v151, v85
	v_fma_f32 v152, v86, v152, v86
	v_fma_f32 v153, v87, v153, v87
	v_mul_f32_e32 v150, 0x3f4c422a, v150
	v_mul_f32_e32 v151, 0x3f4c422a, v151
	v_mul_f32_e32 v152, 0x3f4c422a, v152
	v_mul_f32_e32 v153, 0x3f4c422a, v153
	v_add_f32_e32 v150, v150, v150
	v_add_f32_e32 v151, v151, v151
	v_add_f32_e32 v152, v152, v152
	v_add_f32_e32 v153, v153, v153
	v_mul_f32_e32 v150, 0x3fb8aa3b, v150
	v_mul_f32_e32 v151, 0x3fb8aa3b, v151
	v_mul_f32_e32 v152, 0x3fb8aa3b, v152
	v_mul_f32_e32 v153, 0x3fb8aa3b, v153
	v_exp_f32_e32 v150, v150
	v_exp_f32_e32 v151, v151
	v_exp_f32_e32 v152, v152
	v_exp_f32_e32 v153, v153
	v_add_f32_e32 v150, 1.0, v150
	v_add_f32_e32 v151, 1.0, v151
	v_add_f32_e32 v152, 1.0, v152
	v_add_f32_e32 v153, 1.0, v153
	v_rcp_f32_e32 v150, v150
	v_rcp_f32_e32 v151, v151
	v_rcp_f32_e32 v152, v152
	v_rcp_f32_e32 v153, v153
	v_pk_mul_f32 v[84:85], v[84:85], 0.5 op_sel_hi:[1,0]
	v_pk_mul_f32 v[86:87], v[86:87], 0.5 op_sel_hi:[1,0]
	v_pk_fma_f32 v[150:151], v[150:151], 2.0, 1.0 op_sel_hi:[1,0,0] neg_lo:[1,0,0] neg_hi:[1,0,0]
	v_pk_fma_f32 v[152:153], v[152:153], 2.0, 1.0 op_sel_hi:[1,0,0] neg_lo:[1,0,0] neg_hi:[1,0,0]
	v_pk_add_f32 v[150:151], v[150:151], 1.0 op_sel_hi:[1,0]
	v_pk_add_f32 v[152:153], v[152:153], 1.0 op_sel_hi:[1,0]
	v_pk_mul_f32 v[84:85], v[84:85], v[150:151]
	v_pk_mul_f32 v[86:87], v[86:87], v[152:153]
	s_nop 0
	v_cvt_pk_bf16_f32 v84, v84, v85
	v_cvt_pk_bf16_f32 v85, v86, v87
	global_store_dwordx2 v141, v[84:85], s[78:79]
	s_waitcnt vmcnt(31)
; __device__ __forceinline__ float bflo(unsigned w) { return __uint_as_float(w << 16); }
; __device__ __forceinline__ float bfhi(unsigned w) { return __uint_as_float(w & 0xffff0000u); }
; __device__ __forceinline__ unsigned pk2(float lo, float hi) { return pg8::cvt_pk_bf16(lo, hi); }
; __device__ __forceinline__ float gelu_tanh(float y) { const float a = 0.7978845608028654f * (y + 0.044715f * y * y * y); const float e = __expf(2.0f * a); const float th = 1.0f - 2.0f * __builtin_amdgcn_rcpf(e + 1.0f); return 0.5f * y * (1.0f + th); }
;     __device__ __forceinline__ void operator()(const f32x4 (&acc)[2][2][4][2], const Unit& u, int wr, int wc, int fr, int fq) const {
;     ...
;             for (int m = 0; m < 4; ++m) { const int rowg = mh * 256 + ai * 128 + wr * 64 + m * 16 + fr, b = rowg >> 6, c = rowg & 63;
; #pragma unroll
;                 for (int bj = 0; bj < 2; ++bj)
; #pragma unroll
;                     for (int n = 0; n < 2; ++n) { const int colg = nh * 256 + bj * 128 + wc * 32 + n * 16 + 4 * fq, tau = colg >> 4, ch = g * 16 + (colg & 15);
;                         const size_t tok = (size_t)b * SEQ + 32 * c + tau;
;                         const u32x2 uw = *(const u32x2*)(z + tok * ZP + C_SU + ch); const f32x4 d4 = *(const f32x4*)(dsk + ch); const f32x4 a = acc[ai][bj][m][n];
;                         u32x2 o; o.x = pk2(gelu_tanh(a[0] + d4[0] * bflo(uw.x)), gelu_tanh(a[1] + d4[1] * bfhi(uw.x))); o.y = pk2(gelu_tanh(a[2] + d4[2] * bflo(uw.y)), gelu_tanh(a[3] + d4[3] * bfhi(uw.y)));
;                         *(u32x2*)(ysg + tok * 512 + ch) = o; } }
	v_lshlrev_b32_e32 v150, 16, v198
	v_and_b32_e32 v151, 0xffff0000, v198
	v_lshlrev_b32_e32 v152, 16, v199
	v_and_b32_e32 v153, 0xffff0000, v199
	v_or_b32_e32 v139, s20, v140
	v_pk_fma_f32 v[80:81], v[154:155], v[150:151], v[80:81]
	v_pk_fma_f32 v[82:83], v[156:157], v[152:153], v[82:83]
	v_or_b32_e32 v139, s7, v139
	v_lshl_add_u32 v141, v139, 10, v146
	v_mul_f32_e32 v150, 0x3d372713, v80
	v_mul_f32_e32 v151, 0x3d372713, v81
	v_mul_f32_e32 v152, 0x3d372713, v82
	v_mul_f32_e32 v153, 0x3d372713, v83
	v_mul_f32_e32 v150, v80, v150
	v_mul_f32_e32 v151, v81, v151
	v_mul_f32_e32 v152, v82, v152
	v_mul_f32_e32 v153, v83, v153
	v_fma_f32 v150, v80, v150, v80
	v_fma_f32 v151, v81, v151, v81
	v_fma_f32 v152, v82, v152, v82
	v_fma_f32 v153, v83, v153, v83
	v_mul_f32_e32 v150, 0x3f4c422a, v150
	v_mul_f32_e32 v151, 0x3f4c422a, v151
	v_mul_f32_e32 v152, 0x3f4c422a, v152
	v_mul_f32_e32 v153, 0x3f4c422a, v153
	v_add_f32_e32 v150, v150, v150
	v_add_f32_e32 v151, v151, v151
	v_add_f32_e32 v152, v152, v152
	v_add_f32_e32 v153, v153, v153
	v_mul_f32_e32 v150, 0x3fb8aa3b, v150
	v_mul_f32_e32 v151, 0x3fb8aa3b, v151
	v_mul_f32_e32 v152, 0x3fb8aa3b, v152
	v_mul_f32_e32 v153, 0x3fb8aa3b, v153
	v_exp_f32_e32 v150, v150
	v_exp_f32_e32 v151, v151
	v_exp_f32_e32 v152, v152
	v_exp_f32_e32 v153, v153
	v_add_f32_e32 v150, 1.0, v150
	v_add_f32_e32 v151, 1.0, v151
	v_add_f32_e32 v152, 1.0, v152
	v_add_f32_e32 v153, 1.0, v153
	v_rcp_f32_e32 v150, v150
	v_rcp_f32_e32 v151, v151
	v_rcp_f32_e32 v152, v152
	v_rcp_f32_e32 v153, v153
	v_pk_mul_f32 v[80:81], v[80:81], 0.5 op_sel_hi:[1,0]
	v_pk_mul_f32 v[82:83], v[82:83], 0.5 op_sel_hi:[1,0]
	v_pk_fma_f32 v[150:151], v[150:151], 2.0, 1.0 op_sel_hi:[1,0,0] neg_lo:[1,0,0] neg_hi:[1,0,0]
	v_pk_fma_f32 v[152:153], v[152:153], 2.0, 1.0 op_sel_hi:[1,0,0] neg_lo:[1,0,0] neg_hi:[1,0,0]
	v_pk_add_f32 v[150:151], v[150:151], 1.0 op_sel_hi:[1,0]
	v_pk_add_f32 v[152:153], v[152:153], 1.0 op_sel_hi:[1,0]
	v_pk_mul_f32 v[80:81], v[80:81], v[150:151]
	v_pk_mul_f32 v[82:83], v[82:83], v[152:153]
	s_nop 0
	v_cvt_pk_bf16_f32 v80, v80, v81
	v_cvt_pk_bf16_f32 v81, v82, v83
	global_store_dwordx2 v141, v[80:81], s[78:79]
	s_waitcnt vmcnt(31)
	v_lshlrev_b32_e32 v150, 16, v200
	v_and_b32_e32 v151, 0xffff0000, v200
	v_lshlrev_b32_e32 v152, 16, v201
	v_and_b32_e32 v153, 0xffff0000, v201
	v_or_b32_e32 v139, s20, v140
	v_pk_fma_f32 v[76:77], v[154:155], v[150:151], v[76:77]
	v_pk_fma_f32 v[78:79], v[156:157], v[152:153], v[78:79]
	v_or_b32_e32 v139, s5, v139
	v_lshl_add_u32 v141, v139, 10, v146
	v_mul_f32_e32 v150, 0x3d372713, v76
	v_mul_f32_e32 v151, 0x3d372713, v77
	v_mul_f32_e32 v152, 0x3d372713, v78
	v_mul_f32_e32 v153, 0x3d372713, v79
	v_mul_f32_e32 v150, v76, v150
	v_mul_f32_e32 v151, v77, v151
	v_mul_f32_e32 v152, v78, v152
	v_mul_f32_e32 v153, v79, v153
	v_fma_f32 v150, v76, v150, v76
	v_fma_f32 v151, v77, v151, v77
	v_fma_f32 v152, v78, v152, v78
	v_fma_f32 v153, v79, v153, v79
	v_mul_f32_e32 v150, 0x3f4c422a, v150
	v_mul_f32_e32 v151, 0x3f4c422a, v151
	v_mul_f32_e32 v152, 0x3f4c422a, v152
	v_mul_f32_e32 v153, 0x3f4c422a, v153
	v_add_f32_e32 v150, v150, v150
	v_add_f32_e32 v151, v151, v151
	v_add_f32_e32 v152, v152, v152
	v_add_f32_e32 v153, v153, v153
	v_mul_f32_e32 v150, 0x3fb8aa3b, v150
	v_mul_f32_e32 v151, 0x3fb8aa3b, v151
	v_mul_f32_e32 v152, 0x3fb8aa3b, v152
	v_mul_f32_e32 v153, 0x3fb8aa3b, v153
	v_exp_f32_e32 v150, v150
	v_exp_f32_e32 v151, v151
	v_exp_f32_e32 v152, v152
	v_exp_f32_e32 v153, v153
	v_add_f32_e32 v150, 1.0, v150
	v_add_f32_e32 v151, 1.0, v151
	v_add_f32_e32 v152, 1.0, v152
	v_add_f32_e32 v153, 1.0, v153
	v_rcp_f32_e32 v150, v150
	v_rcp_f32_e32 v151, v151
	v_rcp_f32_e32 v152, v152
	v_rcp_f32_e32 v153, v153
	v_pk_mul_f32 v[76:77], v[76:77], 0.5 op_sel_hi:[1,0]
	v_pk_mul_f32 v[78:79], v[78:79], 0.5 op_sel_hi:[1,0]
	v_pk_fma_f32 v[150:151], v[150:151], 2.0, 1.0 op_sel_hi:[1,0,0] neg_lo:[1,0,0] neg_hi:[1,0,0]
	v_pk_fma_f32 v[152:153], v[152:153], 2.0, 1.0 op_sel_hi:[1,0,0] neg_lo:[1,0,0] neg_hi:[1,0,0]
	v_pk_add_f32 v[150:151], v[150:151], 1.0 op_sel_hi:[1,0]
	v_pk_add_f32 v[152:153], v[152:153], 1.0 op_sel_hi:[1,0]
	v_pk_mul_f32 v[76:77], v[76:77], v[150:151]
	v_pk_mul_f32 v[78:79], v[78:79], v[152:153]
	s_nop 0
	v_cvt_pk_bf16_f32 v76, v76, v77
	v_cvt_pk_bf16_f32 v77, v78, v79
	global_store_dwordx2 v141, v[76:77], s[78:79]
	s_waitcnt vmcnt(31)
	v_lshlrev_b32_e32 v150, 16, v202
	v_and_b32_e32 v151, 0xffff0000, v202
	v_lshlrev_b32_e32 v152, 16, v203
	v_and_b32_e32 v153, 0xffff0000, v203
	v_or_b32_e32 v139, s20, v140
	v_pk_fma_f32 v[72:73], v[154:155], v[150:151], v[72:73]
	v_pk_fma_f32 v[74:75], v[156:157], v[152:153], v[74:75]
	v_or_b32_e32 v139, s4, v139
	v_lshl_add_u32 v141, v139, 10, v146
	v_mul_f32_e32 v150, 0x3d372713, v72
	v_mul_f32_e32 v151, 0x3d372713, v73
	v_mul_f32_e32 v152, 0x3d372713, v74
	v_mul_f32_e32 v153, 0x3d372713, v75
	v_mul_f32_e32 v150, v72, v150
	v_mul_f32_e32 v151, v73, v151
	v_mul_f32_e32 v152, v74, v152
	v_mul_f32_e32 v153, v75, v153
	v_fma_f32 v150, v72, v150, v72
	v_fma_f32 v151, v73, v151, v73
	v_fma_f32 v152, v74, v152, v74
	v_fma_f32 v153, v75, v153, v75
	v_mul_f32_e32 v150, 0x3f4c422a, v150
	v_mul_f32_e32 v151, 0x3f4c422a, v151
	v_mul_f32_e32 v152, 0x3f4c422a, v152
	v_mul_f32_e32 v153, 0x3f4c422a, v153
	v_add_f32_e32 v150, v150, v150
	v_add_f32_e32 v151, v151, v151
	v_add_f32_e32 v152, v152, v152
	v_add_f32_e32 v153, v153, v153
	v_mul_f32_e32 v150, 0x3fb8aa3b, v150
	v_mul_f32_e32 v151, 0x3fb8aa3b, v151
	v_mul_f32_e32 v152, 0x3fb8aa3b, v152
	v_mul_f32_e32 v153, 0x3fb8aa3b, v153
	v_exp_f32_e32 v150, v150
	v_exp_f32_e32 v151, v151
	v_exp_f32_e32 v152, v152
	v_exp_f32_e32 v153, v153
	v_add_f32_e32 v150, 1.0, v150
	v_add_f32_e32 v151, 1.0, v151
	v_add_f32_e32 v152, 1.0, v152
	v_add_f32_e32 v153, 1.0, v153
	v_rcp_f32_e32 v150, v150
	v_rcp_f32_e32 v151, v151
	v_rcp_f32_e32 v152, v152
	v_rcp_f32_e32 v153, v153
	v_pk_mul_f32 v[72:73], v[72:73], 0.5 op_sel_hi:[1,0]
	v_pk_mul_f32 v[74:75], v[74:75], 0.5 op_sel_hi:[1,0]
	v_pk_fma_f32 v[150:151], v[150:151], 2.0, 1.0 op_sel_hi:[1,0,0] neg_lo:[1,0,0] neg_hi:[1,0,0]
	v_pk_fma_f32 v[152:153], v[152:153], 2.0, 1.0 op_sel_hi:[1,0,0] neg_lo:[1,0,0] neg_hi:[1,0,0]
	v_pk_add_f32 v[150:151], v[150:151], 1.0 op_sel_hi:[1,0]
	v_pk_add_f32 v[152:153], v[152:153], 1.0 op_sel_hi:[1,0]
	v_pk_mul_f32 v[72:73], v[72:73], v[150:151]
	v_pk_mul_f32 v[74:75], v[74:75], v[152:153]
	s_nop 0
	v_cvt_pk_bf16_f32 v72, v72, v73
	v_cvt_pk_bf16_f32 v73, v74, v75
	global_store_dwordx2 v141, v[72:73], s[78:79]
	s_waitcnt vmcnt(31)
; __device__ __forceinline__ float bflo(unsigned w) { return __uint_as_float(w << 16); }
; __device__ __forceinline__ float bfhi(unsigned w) { return __uint_as_float(w & 0xffff0000u); }
; __device__ __forceinline__ unsigned pk2(float lo, float hi) { return pg8::cvt_pk_bf16(lo, hi); }
; __device__ __forceinline__ float gelu_tanh(float y) { const float a = 0.7978845608028654f * (y + 0.044715f * y * y * y); const float e = __expf(2.0f * a); const float th = 1.0f - 2.0f * __builtin_amdgcn_rcpf(e + 1.0f); return 0.5f * y * (1.0f + th); }
;     __device__ __forceinline__ void operator()(const f32x4 (&acc)[2][2][4][2], const Unit& u, int wr, int wc, int fr, int fq) const {
;     ...
;             for (int m = 0; m < 4; ++m) { const int rowg = mh * 256 + ai * 128 + wr * 64 + m * 16 + fr, b = rowg >> 6, c = rowg & 63;
; #pragma unroll
;                 for (int bj = 0; bj < 2; ++bj)
; #pragma unroll
;                     for (int n = 0; n < 2; ++n) { const int colg = nh * 256 + bj * 128 + wc * 32 + n * 16 + 4 * fq, tau = colg >> 4, ch = g * 16 + (colg & 15);
;                         const size_t tok = (size_t)b * SEQ + 32 * c + tau;
;                         const u32x2 uw = *(const u32x2*)(z + tok * ZP + C_SU + ch); const f32x4 d4 = *(const f32x4*)(dsk + ch); const f32x4 a = acc[ai][bj][m][n];
;                         u32x2 o; o.x = pk2(gelu_tanh(a[0] + d4[0] * bflo(uw.x)), gelu_tanh(a[1] + d4[1] * bfhi(uw.x))); o.y = pk2(gelu_tanh(a[2] + d4[2] * bflo(uw.y)), gelu_tanh(a[3] + d4[3] * bfhi(uw.y)));
;                         *(u32x2*)(ysg + tok * 512 + ch) = o; } }
	v_lshlrev_b32_e32 v150, 16, v204
	v_and_b32_e32 v151, 0xffff0000, v204
	v_lshlrev_b32_e32 v152, 16, v205
	v_and_b32_e32 v153, 0xffff0000, v205
	v_or_b32_e32 v139, s20, v140
	v_pk_fma_f32 v[68:69], v[154:155], v[150:151], v[68:69]
	v_pk_fma_f32 v[70:71], v[156:157], v[152:153], v[70:71]
	v_or_b32_e32 v139, s6, v139
	v_lshl_add_u32 v141, v139, 10, v146
	v_mul_f32_e32 v150, 0x3d372713, v68
	v_mul_f32_e32 v151, 0x3d372713, v69
	v_mul_f32_e32 v152, 0x3d372713, v70
	v_mul_f32_e32 v153, 0x3d372713, v71
	v_mul_f32_e32 v150, v68, v150
	v_mul_f32_e32 v151, v69, v151
	v_mul_f32_e32 v152, v70, v152
	v_mul_f32_e32 v153, v71, v153
	v_fma_f32 v150, v68, v150, v68
	v_fma_f32 v151, v69, v151, v69
	v_fma_f32 v152, v70, v152, v70
	v_fma_f32 v153, v71, v153, v71
	v_mul_f32_e32 v150, 0x3f4c422a, v150
	v_mul_f32_e32 v151, 0x3f4c422a, v151
	v_mul_f32_e32 v152, 0x3f4c422a, v152
	v_mul_f32_e32 v153, 0x3f4c422a, v153
	v_add_f32_e32 v150, v150, v150
	v_add_f32_e32 v151, v151, v151
	v_add_f32_e32 v152, v152, v152
	v_add_f32_e32 v153, v153, v153
	v_mul_f32_e32 v150, 0x3fb8aa3b, v150
	v_mul_f32_e32 v151, 0x3fb8aa3b, v151
	v_mul_f32_e32 v152, 0x3fb8aa3b, v152
	v_mul_f32_e32 v153, 0x3fb8aa3b, v153
	v_exp_f32_e32 v150, v150
	v_exp_f32_e32 v151, v151
	v_exp_f32_e32 v152, v152
	v_exp_f32_e32 v153, v153
	v_add_f32_e32 v150, 1.0, v150
	v_add_f32_e32 v151, 1.0, v151
	v_add_f32_e32 v152, 1.0, v152
	v_add_f32_e32 v153, 1.0, v153
	v_rcp_f32_e32 v150, v150
	v_rcp_f32_e32 v151, v151
	v_rcp_f32_e32 v152, v152
	v_rcp_f32_e32 v153, v153
	v_pk_mul_f32 v[68:69], v[68:69], 0.5 op_sel_hi:[1,0]
	v_pk_mul_f32 v[70:71], v[70:71], 0.5 op_sel_hi:[1,0]
	v_pk_fma_f32 v[150:151], v[150:151], 2.0, 1.0 op_sel_hi:[1,0,0] neg_lo:[1,0,0] neg_hi:[1,0,0]
	v_pk_fma_f32 v[152:153], v[152:153], 2.0, 1.0 op_sel_hi:[1,0,0] neg_lo:[1,0,0] neg_hi:[1,0,0]
	v_pk_add_f32 v[150:151], v[150:151], 1.0 op_sel_hi:[1,0]
	v_pk_add_f32 v[152:153], v[152:153], 1.0 op_sel_hi:[1,0]
	v_pk_mul_f32 v[68:69], v[68:69], v[150:151]
	v_pk_mul_f32 v[70:71], v[70:71], v[152:153]
	s_nop 0
	v_cvt_pk_bf16_f32 v68, v68, v69
	v_cvt_pk_bf16_f32 v69, v70, v71
	global_store_dwordx2 v141, v[68:69], s[78:79]
	s_waitcnt vmcnt(23)
	v_lshlrev_b32_e32 v150, 16, v128
	v_and_b32_e32 v151, 0xffff0000, v128
	v_lshlrev_b32_e32 v152, 16, v129
	v_and_b32_e32 v153, 0xffff0000, v129
	v_or_b32_e32 v139, s22, v134
	v_pk_fma_f32 v[64:65], v[154:155], v[150:151], v[64:65]
	v_pk_fma_f32 v[66:67], v[156:157], v[152:153], v[66:67]
	v_or_b32_e32 v139, s7, v139
	v_lshl_add_u32 v141, v139, 10, v146
	v_mul_f32_e32 v150, 0x3d372713, v64
	v_mul_f32_e32 v151, 0x3d372713, v65
	v_mul_f32_e32 v152, 0x3d372713, v66
	v_mul_f32_e32 v153, 0x3d372713, v67
	v_mul_f32_e32 v150, v64, v150
	v_mul_f32_e32 v151, v65, v151
	v_mul_f32_e32 v152, v66, v152
	v_mul_f32_e32 v153, v67, v153
	v_fma_f32 v150, v64, v150, v64
	v_fma_f32 v151, v65, v151, v65
	v_fma_f32 v152, v66, v152, v66
	v_fma_f32 v153, v67, v153, v67
	v_mul_f32_e32 v150, 0x3f4c422a, v150
	v_mul_f32_e32 v151, 0x3f4c422a, v151
	v_mul_f32_e32 v152, 0x3f4c422a, v152
	v_mul_f32_e32 v153, 0x3f4c422a, v153
	v_add_f32_e32 v150, v150, v150
	v_add_f32_e32 v151, v151, v151
	v_add_f32_e32 v152, v152, v152
	v_add_f32_e32 v153, v153, v153
	v_mul_f32_e32 v150, 0x3fb8aa3b, v150
	v_mul_f32_e32 v151, 0x3fb8aa3b, v151
	v_mul_f32_e32 v152, 0x3fb8aa3b, v152
	v_mul_f32_e32 v153, 0x3fb8aa3b, v153
	v_exp_f32_e32 v150, v150
	v_exp_f32_e32 v151, v151
	v_exp_f32_e32 v152, v152
	v_exp_f32_e32 v153, v153
	v_add_f32_e32 v150, 1.0, v150
	v_add_f32_e32 v151, 1.0, v151
	v_add_f32_e32 v152, 1.0, v152
	v_add_f32_e32 v153, 1.0, v153
	v_rcp_f32_e32 v150, v150
	v_rcp_f32_e32 v151, v151
	v_rcp_f32_e32 v152, v152
	v_rcp_f32_e32 v153, v153
	v_pk_mul_f32 v[64:65], v[64:65], 0.5 op_sel_hi:[1,0]
	v_pk_mul_f32 v[66:67], v[66:67], 0.5 op_sel_hi:[1,0]
	v_pk_fma_f32 v[150:151], v[150:151], 2.0, 1.0 op_sel_hi:[1,0,0] neg_lo:[1,0,0] neg_hi:[1,0,0]
	v_pk_fma_f32 v[152:153], v[152:153], 2.0, 1.0 op_sel_hi:[1,0,0] neg_lo:[1,0,0] neg_hi:[1,0,0]
	v_pk_add_f32 v[150:151], v[150:151], 1.0 op_sel_hi:[1,0]
	v_pk_add_f32 v[152:153], v[152:153], 1.0 op_sel_hi:[1,0]
	v_pk_mul_f32 v[64:65], v[64:65], v[150:151]
	v_pk_mul_f32 v[66:67], v[66:67], v[152:153]
	s_nop 0
	v_cvt_pk_bf16_f32 v64, v64, v65
	v_cvt_pk_bf16_f32 v65, v66, v67
	global_store_dwordx2 v141, v[64:65], s[78:79]
	s_waitcnt vmcnt(23)
	v_lshlrev_b32_e32 v150, 16, v130
	v_and_b32_e32 v151, 0xffff0000, v130
	v_lshlrev_b32_e32 v152, 16, v131
	v_and_b32_e32 v153, 0xffff0000, v131
	v_or_b32_e32 v139, s22, v134
	v_pk_fma_f32 v[60:61], v[154:155], v[150:151], v[60:61]
	v_pk_fma_f32 v[62:63], v[156:157], v[152:153], v[62:63]
	v_or_b32_e32 v139, s5, v139
	v_lshl_add_u32 v141, v139, 10, v146
	v_mul_f32_e32 v150, 0x3d372713, v60
	v_mul_f32_e32 v151, 0x3d372713, v61
	v_mul_f32_e32 v152, 0x3d372713, v62
	v_mul_f32_e32 v153, 0x3d372713, v63
	v_mul_f32_e32 v150, v60, v150
	v_mul_f32_e32 v151, v61, v151
	v_mul_f32_e32 v152, v62, v152
	v_mul_f32_e32 v153, v63, v153
	v_fma_f32 v150, v60, v150, v60
	v_fma_f32 v151, v61, v151, v61
	v_fma_f32 v152, v62, v152, v62
	v_fma_f32 v153, v63, v153, v63
	v_mul_f32_e32 v150, 0x3f4c422a, v150
	v_mul_f32_e32 v151, 0x3f4c422a, v151
	v_mul_f32_e32 v152, 0x3f4c422a, v152
	v_mul_f32_e32 v153, 0x3f4c422a, v153
	v_add_f32_e32 v150, v150, v150
	v_add_f32_e32 v151, v151, v151
	v_add_f32_e32 v152, v152, v152
	v_add_f32_e32 v153, v153, v153
	v_mul_f32_e32 v150, 0x3fb8aa3b, v150
	v_mul_f32_e32 v151, 0x3fb8aa3b, v151
	v_mul_f32_e32 v152, 0x3fb8aa3b, v152
	v_mul_f32_e32 v153, 0x3fb8aa3b, v153
	v_exp_f32_e32 v150, v150
	v_exp_f32_e32 v151, v151
	v_exp_f32_e32 v152, v152
	v_exp_f32_e32 v153, v153
	v_add_f32_e32 v150, 1.0, v150
	v_add_f32_e32 v151, 1.0, v151
	v_add_f32_e32 v152, 1.0, v152
	v_add_f32_e32 v153, 1.0, v153
	v_rcp_f32_e32 v150, v150
	v_rcp_f32_e32 v151, v151
	v_rcp_f32_e32 v152, v152
	v_rcp_f32_e32 v153, v153
	v_pk_mul_f32 v[60:61], v[60:61], 0.5 op_sel_hi:[1,0]
	v_pk_mul_f32 v[62:63], v[62:63], 0.5 op_sel_hi:[1,0]
	v_pk_fma_f32 v[150:151], v[150:151], 2.0, 1.0 op_sel_hi:[1,0,0] neg_lo:[1,0,0] neg_hi:[1,0,0]
	v_pk_fma_f32 v[152:153], v[152:153], 2.0, 1.0 op_sel_hi:[1,0,0] neg_lo:[1,0,0] neg_hi:[1,0,0]
	v_pk_add_f32 v[150:151], v[150:151], 1.0 op_sel_hi:[1,0]
	v_pk_add_f32 v[152:153], v[152:153], 1.0 op_sel_hi:[1,0]
	v_pk_mul_f32 v[60:61], v[60:61], v[150:151]
	v_pk_mul_f32 v[62:63], v[62:63], v[152:153]
	s_nop 0
	v_cvt_pk_bf16_f32 v60, v60, v61
	v_cvt_pk_bf16_f32 v61, v62, v63
	global_store_dwordx2 v141, v[60:61], s[78:79]
	s_waitcnt vmcnt(23)
; __device__ __forceinline__ float bflo(unsigned w) { return __uint_as_float(w << 16); }
; __device__ __forceinline__ float bfhi(unsigned w) { return __uint_as_float(w & 0xffff0000u); }
; __device__ __forceinline__ unsigned pk2(float lo, float hi) { return pg8::cvt_pk_bf16(lo, hi); }
; __device__ __forceinline__ float gelu_tanh(float y) { const float a = 0.7978845608028654f * (y + 0.044715f * y * y * y); const float e = __expf(2.0f * a); const float th = 1.0f - 2.0f * __builtin_amdgcn_rcpf(e + 1.0f); return 0.5f * y * (1.0f + th); }
;     __device__ __forceinline__ void operator()(const f32x4 (&acc)[2][2][4][2], const Unit& u, int wr, int wc, int fr, int fq) const {
;     ...
;             for (int m = 0; m < 4; ++m) { const int rowg = mh * 256 + ai * 128 + wr * 64 + m * 16 + fr, b = rowg >> 6, c = rowg & 63;
; #pragma unroll
;                 for (int bj = 0; bj < 2; ++bj)
; #pragma unroll
;                     for (int n = 0; n < 2; ++n) { const int colg = nh * 256 + bj * 128 + wc * 32 + n * 16 + 4 * fq, tau = colg >> 4, ch = g * 16 + (colg & 15);
;                         const size_t tok = (size_t)b * SEQ + 32 * c + tau;
;                         const u32x2 uw = *(const u32x2*)(z + tok * ZP + C_SU + ch); const f32x4 d4 = *(const f32x4*)(dsk + ch); const f32x4 a = acc[ai][bj][m][n];
;                         u32x2 o; o.x = pk2(gelu_tanh(a[0] + d4[0] * bflo(uw.x)), gelu_tanh(a[1] + d4[1] * bfhi(uw.x))); o.y = pk2(gelu_tanh(a[2] + d4[2] * bflo(uw.y)), gelu_tanh(a[3] + d4[3] * bfhi(uw.y)));
;                         *(u32x2*)(ysg + tok * 512 + ch) = o; } }
	v_lshlrev_b32_e32 v150, 16, v124
	v_and_b32_e32 v151, 0xffff0000, v124
	v_lshlrev_b32_e32 v152, 16, v125
	v_and_b32_e32 v153, 0xffff0000, v125
	v_or_b32_e32 v139, s22, v134
	v_pk_fma_f32 v[56:57], v[154:155], v[150:151], v[56:57]
	v_pk_fma_f32 v[58:59], v[156:157], v[152:153], v[58:59]
	v_or_b32_e32 v139, s4, v139
	v_lshl_add_u32 v141, v139, 10, v146
	v_mul_f32_e32 v150, 0x3d372713, v56
	v_mul_f32_e32 v151, 0x3d372713, v57
	v_mul_f32_e32 v152, 0x3d372713, v58
	v_mul_f32_e32 v153, 0x3d372713, v59
	v_mul_f32_e32 v150, v56, v150
	v_mul_f32_e32 v151, v57, v151
	v_mul_f32_e32 v152, v58, v152
	v_mul_f32_e32 v153, v59, v153
	v_fma_f32 v150, v56, v150, v56
	v_fma_f32 v151, v57, v151, v57
	v_fma_f32 v152, v58, v152, v58
	v_fma_f32 v153, v59, v153, v59
	v_mul_f32_e32 v150, 0x3f4c422a, v150
	v_mul_f32_e32 v151, 0x3f4c422a, v151
	v_mul_f32_e32 v152, 0x3f4c422a, v152
	v_mul_f32_e32 v153, 0x3f4c422a, v153
	v_add_f32_e32 v150, v150, v150
	v_add_f32_e32 v151, v151, v151
	v_add_f32_e32 v152, v152, v152
	v_add_f32_e32 v153, v153, v153
	v_mul_f32_e32 v150, 0x3fb8aa3b, v150
	v_mul_f32_e32 v151, 0x3fb8aa3b, v151
	v_mul_f32_e32 v152, 0x3fb8aa3b, v152
	v_mul_f32_e32 v153, 0x3fb8aa3b, v153
	v_exp_f32_e32 v150, v150
	v_exp_f32_e32 v151, v151
	v_exp_f32_e32 v152, v152
	v_exp_f32_e32 v153, v153
	v_add_f32_e32 v150, 1.0, v150
	v_add_f32_e32 v151, 1.0, v151
	v_add_f32_e32 v152, 1.0, v152
	v_add_f32_e32 v153, 1.0, v153
	v_rcp_f32_e32 v150, v150
	v_rcp_f32_e32 v151, v151
	v_rcp_f32_e32 v152, v152
	v_rcp_f32_e32 v153, v153
	v_pk_mul_f32 v[56:57], v[56:57], 0.5 op_sel_hi:[1,0]
	v_pk_mul_f32 v[58:59], v[58:59], 0.5 op_sel_hi:[1,0]
	v_pk_fma_f32 v[150:151], v[150:151], 2.0, 1.0 op_sel_hi:[1,0,0] neg_lo:[1,0,0] neg_hi:[1,0,0]
	v_pk_fma_f32 v[152:153], v[152:153], 2.0, 1.0 op_sel_hi:[1,0,0] neg_lo:[1,0,0] neg_hi:[1,0,0]
	v_pk_add_f32 v[150:151], v[150:151], 1.0 op_sel_hi:[1,0]
	v_pk_add_f32 v[152:153], v[152:153], 1.0 op_sel_hi:[1,0]
	v_pk_mul_f32 v[56:57], v[56:57], v[150:151]
	v_pk_mul_f32 v[58:59], v[58:59], v[152:153]
	s_nop 0
	v_cvt_pk_bf16_f32 v56, v56, v57
	v_cvt_pk_bf16_f32 v57, v58, v59
	global_store_dwordx2 v141, v[56:57], s[78:79]
	s_waitcnt vmcnt(23)
	v_lshlrev_b32_e32 v150, 16, v126
	v_and_b32_e32 v151, 0xffff0000, v126
	v_lshlrev_b32_e32 v152, 16, v127
	v_and_b32_e32 v153, 0xffff0000, v127
	v_or_b32_e32 v139, s22, v134
	v_pk_fma_f32 v[52:53], v[154:155], v[150:151], v[52:53]
	v_pk_fma_f32 v[54:55], v[156:157], v[152:153], v[54:55]
	v_or_b32_e32 v139, s6, v139
	v_lshl_add_u32 v141, v139, 10, v146
	v_mul_f32_e32 v150, 0x3d372713, v52
	v_mul_f32_e32 v151, 0x3d372713, v53
	v_mul_f32_e32 v152, 0x3d372713, v54
	v_mul_f32_e32 v153, 0x3d372713, v55
	v_mul_f32_e32 v150, v52, v150
	v_mul_f32_e32 v151, v53, v151
	v_mul_f32_e32 v152, v54, v152
	v_mul_f32_e32 v153, v55, v153
	v_fma_f32 v150, v52, v150, v52
	v_fma_f32 v151, v53, v151, v53
	v_fma_f32 v152, v54, v152, v54
	v_fma_f32 v153, v55, v153, v55
	v_mul_f32_e32 v150, 0x3f4c422a, v150
	v_mul_f32_e32 v151, 0x3f4c422a, v151
	v_mul_f32_e32 v152, 0x3f4c422a, v152
	v_mul_f32_e32 v153, 0x3f4c422a, v153
	v_add_f32_e32 v150, v150, v150
	v_add_f32_e32 v151, v151, v151
	v_add_f32_e32 v152, v152, v152
	v_add_f32_e32 v153, v153, v153
	v_mul_f32_e32 v150, 0x3fb8aa3b, v150
	v_mul_f32_e32 v151, 0x3fb8aa3b, v151
	v_mul_f32_e32 v152, 0x3fb8aa3b, v152
	v_mul_f32_e32 v153, 0x3fb8aa3b, v153
	v_exp_f32_e32 v150, v150
	v_exp_f32_e32 v151, v151
	v_exp_f32_e32 v152, v152
	v_exp_f32_e32 v153, v153
	v_add_f32_e32 v150, 1.0, v150
	v_add_f32_e32 v151, 1.0, v151
	v_add_f32_e32 v152, 1.0, v152
	v_add_f32_e32 v153, 1.0, v153
	v_rcp_f32_e32 v150, v150
	v_rcp_f32_e32 v151, v151
	v_rcp_f32_e32 v152, v152
	v_rcp_f32_e32 v153, v153
	v_pk_mul_f32 v[52:53], v[52:53], 0.5 op_sel_hi:[1,0]
	v_pk_mul_f32 v[54:55], v[54:55], 0.5 op_sel_hi:[1,0]
	v_pk_fma_f32 v[150:151], v[150:151], 2.0, 1.0 op_sel_hi:[1,0,0] neg_lo:[1,0,0] neg_hi:[1,0,0]
	v_pk_fma_f32 v[152:153], v[152:153], 2.0, 1.0 op_sel_hi:[1,0,0] neg_lo:[1,0,0] neg_hi:[1,0,0]
	v_pk_add_f32 v[150:151], v[150:151], 1.0 op_sel_hi:[1,0]
	v_pk_add_f32 v[152:153], v[152:153], 1.0 op_sel_hi:[1,0]
	v_pk_mul_f32 v[52:53], v[52:53], v[150:151]
	v_pk_mul_f32 v[54:55], v[54:55], v[152:153]
	s_nop 0
	v_cvt_pk_bf16_f32 v52, v52, v53
	v_cvt_pk_bf16_f32 v53, v54, v55
	global_store_dwordx2 v141, v[52:53], s[78:79]
	s_waitcnt vmcnt(23)
	v_lshlrev_b32_e32 v150, 16, v120
	v_and_b32_e32 v151, 0xffff0000, v120
	v_lshlrev_b32_e32 v152, 16, v121
	v_and_b32_e32 v153, 0xffff0000, v121
	v_or_b32_e32 v139, s22, v136
	v_pk_fma_f32 v[48:49], v[154:155], v[150:151], v[48:49]
	v_pk_fma_f32 v[50:51], v[156:157], v[152:153], v[50:51]
	v_or_b32_e32 v139, s7, v139
	v_lshl_add_u32 v141, v139, 10, v146
	v_mul_f32_e32 v150, 0x3d372713, v48
	v_mul_f32_e32 v151, 0x3d372713, v49
	v_mul_f32_e32 v152, 0x3d372713, v50
	v_mul_f32_e32 v153, 0x3d372713, v51
	v_mul_f32_e32 v150, v48, v150
	v_mul_f32_e32 v151, v49, v151
	v_mul_f32_e32 v152, v50, v152
	v_mul_f32_e32 v153, v51, v153
	v_fma_f32 v150, v48, v150, v48
	v_fma_f32 v151, v49, v151, v49
	v_fma_f32 v152, v50, v152, v50
	v_fma_f32 v153, v51, v153, v51
	v_mul_f32_e32 v150, 0x3f4c422a, v150
	v_mul_f32_e32 v151, 0x3f4c422a, v151
	v_mul_f32_e32 v152, 0x3f4c422a, v152
	v_mul_f32_e32 v153, 0x3f4c422a, v153
	v_add_f32_e32 v150, v150, v150
	v_add_f32_e32 v151, v151, v151
	v_add_f32_e32 v152, v152, v152
	v_add_f32_e32 v153, v153, v153
	v_mul_f32_e32 v150, 0x3fb8aa3b, v150
	v_mul_f32_e32 v151, 0x3fb8aa3b, v151
	v_mul_f32_e32 v152, 0x3fb8aa3b, v152
	v_mul_f32_e32 v153, 0x3fb8aa3b, v153
	v_exp_f32_e32 v150, v150
	v_exp_f32_e32 v151, v151
	v_exp_f32_e32 v152, v152
	v_exp_f32_e32 v153, v153
	v_add_f32_e32 v150, 1.0, v150
	v_add_f32_e32 v151, 1.0, v151
	v_add_f32_e32 v152, 1.0, v152
	v_add_f32_e32 v153, 1.0, v153
	v_rcp_f32_e32 v150, v150
	v_rcp_f32_e32 v151, v151
	v_rcp_f32_e32 v152, v152
	v_rcp_f32_e32 v153, v153
	v_pk_mul_f32 v[48:49], v[48:49], 0.5 op_sel_hi:[1,0]
	v_pk_mul_f32 v[50:51], v[50:51], 0.5 op_sel_hi:[1,0]
	v_pk_fma_f32 v[150:151], v[150:151], 2.0, 1.0 op_sel_hi:[1,0,0] neg_lo:[1,0,0] neg_hi:[1,0,0]
	v_pk_fma_f32 v[152:153], v[152:153], 2.0, 1.0 op_sel_hi:[1,0,0] neg_lo:[1,0,0] neg_hi:[1,0,0]
	v_pk_add_f32 v[150:151], v[150:151], 1.0 op_sel_hi:[1,0]
	v_pk_add_f32 v[152:153], v[152:153], 1.0 op_sel_hi:[1,0]
	v_pk_mul_f32 v[48:49], v[48:49], v[150:151]
	v_pk_mul_f32 v[50:51], v[50:51], v[152:153]
	s_nop 0
	v_cvt_pk_bf16_f32 v48, v48, v49
	v_cvt_pk_bf16_f32 v49, v50, v51
	global_store_dwordx2 v141, v[48:49], s[78:79]
	s_waitcnt vmcnt(23)
; __device__ __forceinline__ float bflo(unsigned w) { return __uint_as_float(w << 16); }
; __device__ __forceinline__ float bfhi(unsigned w) { return __uint_as_float(w & 0xffff0000u); }
; __device__ __forceinline__ unsigned pk2(float lo, float hi) { return pg8::cvt_pk_bf16(lo, hi); }
; __device__ __forceinline__ float gelu_tanh(float y) { const float a = 0.7978845608028654f * (y + 0.044715f * y * y * y); const float e = __expf(2.0f * a); const float th = 1.0f - 2.0f * __builtin_amdgcn_rcpf(e + 1.0f); return 0.5f * y * (1.0f + th); }
;     __device__ __forceinline__ void operator()(const f32x4 (&acc)[2][2][4][2], const Unit& u, int wr, int wc, int fr, int fq) const {
;     ...
;             for (int m = 0; m < 4; ++m) { const int rowg = mh * 256 + ai * 128 + wr * 64 + m * 16 + fr, b = rowg >> 6, c = rowg & 63;
; #pragma unroll
;                 for (int bj = 0; bj < 2; ++bj)
; #pragma unroll
;                     for (int n = 0; n < 2; ++n) { const int colg = nh * 256 + bj * 128 + wc * 32 + n * 16 + 4 * fq, tau = colg >> 4, ch = g * 16 + (colg & 15);
;                         const size_t tok = (size_t)b * SEQ + 32 * c + tau;
;                         const u32x2 uw = *(const u32x2*)(z + tok * ZP + C_SU + ch); const f32x4 d4 = *(const f32x4*)(dsk + ch); const f32x4 a = acc[ai][bj][m][n];
;                         u32x2 o; o.x = pk2(gelu_tanh(a[0] + d4[0] * bflo(uw.x)), gelu_tanh(a[1] + d4[1] * bfhi(uw.x))); o.y = pk2(gelu_tanh(a[2] + d4[2] * bflo(uw.y)), gelu_tanh(a[3] + d4[3] * bfhi(uw.y)));
;                         *(u32x2*)(ysg + tok * 512 + ch) = o; } }
	v_lshlrev_b32_e32 v150, 16, v122
	v_and_b32_e32 v151, 0xffff0000, v122
	v_lshlrev_b32_e32 v152, 16, v123
	v_and_b32_e32 v153, 0xffff0000, v123
	v_or_b32_e32 v139, s22, v136
	v_pk_fma_f32 v[44:45], v[154:155], v[150:151], v[44:45]
	v_pk_fma_f32 v[46:47], v[156:157], v[152:153], v[46:47]
	v_or_b32_e32 v139, s5, v139
	v_lshl_add_u32 v141, v139, 10, v146
	v_mul_f32_e32 v150, 0x3d372713, v44
	v_mul_f32_e32 v151, 0x3d372713, v45
	v_mul_f32_e32 v152, 0x3d372713, v46
	v_mul_f32_e32 v153, 0x3d372713, v47
	v_mul_f32_e32 v150, v44, v150
	v_mul_f32_e32 v151, v45, v151
	v_mul_f32_e32 v152, v46, v152
	v_mul_f32_e32 v153, v47, v153
	v_fma_f32 v150, v44, v150, v44
	v_fma_f32 v151, v45, v151, v45
	v_fma_f32 v152, v46, v152, v46
	v_fma_f32 v153, v47, v153, v47
	v_mul_f32_e32 v150, 0x3f4c422a, v150
	v_mul_f32_e32 v151, 0x3f4c422a, v151
	v_mul_f32_e32 v152, 0x3f4c422a, v152
	v_mul_f32_e32 v153, 0x3f4c422a, v153
	v_add_f32_e32 v150, v150, v150
	v_add_f32_e32 v151, v151, v151
	v_add_f32_e32 v152, v152, v152
	v_add_f32_e32 v153, v153, v153
	v_mul_f32_e32 v150, 0x3fb8aa3b, v150
	v_mul_f32_e32 v151, 0x3fb8aa3b, v151
	v_mul_f32_e32 v152, 0x3fb8aa3b, v152
	v_mul_f32_e32 v153, 0x3fb8aa3b, v153
	v_exp_f32_e32 v150, v150
	v_exp_f32_e32 v151, v151
	v_exp_f32_e32 v152, v152
	v_exp_f32_e32 v153, v153
	v_add_f32_e32 v150, 1.0, v150
	v_add_f32_e32 v151, 1.0, v151
	v_add_f32_e32 v152, 1.0, v152
	v_add_f32_e32 v153, 1.0, v153
	v_rcp_f32_e32 v150, v150
	v_rcp_f32_e32 v151, v151
	v_rcp_f32_e32 v152, v152
	v_rcp_f32_e32 v153, v153
	v_pk_mul_f32 v[44:45], v[44:45], 0.5 op_sel_hi:[1,0]
	v_pk_mul_f32 v[46:47], v[46:47], 0.5 op_sel_hi:[1,0]
	v_pk_fma_f32 v[150:151], v[150:151], 2.0, 1.0 op_sel_hi:[1,0,0] neg_lo:[1,0,0] neg_hi:[1,0,0]
	v_pk_fma_f32 v[152:153], v[152:153], 2.0, 1.0 op_sel_hi:[1,0,0] neg_lo:[1,0,0] neg_hi:[1,0,0]
	v_pk_add_f32 v[150:151], v[150:151], 1.0 op_sel_hi:[1,0]
	v_pk_add_f32 v[152:153], v[152:153], 1.0 op_sel_hi:[1,0]
	v_pk_mul_f32 v[44:45], v[44:45], v[150:151]
	v_pk_mul_f32 v[46:47], v[46:47], v[152:153]
	s_nop 0
	v_cvt_pk_bf16_f32 v44, v44, v45
	v_cvt_pk_bf16_f32 v45, v46, v47
	global_store_dwordx2 v141, v[44:45], s[78:79]
	s_waitcnt vmcnt(23)
	v_lshlrev_b32_e32 v150, 16, v116
	v_and_b32_e32 v151, 0xffff0000, v116
	v_lshlrev_b32_e32 v152, 16, v117
	v_and_b32_e32 v153, 0xffff0000, v117
	v_or_b32_e32 v139, s22, v136
	v_pk_fma_f32 v[40:41], v[154:155], v[150:151], v[40:41]
	v_pk_fma_f32 v[42:43], v[156:157], v[152:153], v[42:43]
	v_or_b32_e32 v139, s4, v139
	v_lshl_add_u32 v141, v139, 10, v146
	v_mul_f32_e32 v150, 0x3d372713, v40
	v_mul_f32_e32 v151, 0x3d372713, v41
	v_mul_f32_e32 v152, 0x3d372713, v42
	v_mul_f32_e32 v153, 0x3d372713, v43
	v_mul_f32_e32 v150, v40, v150
	v_mul_f32_e32 v151, v41, v151
	v_mul_f32_e32 v152, v42, v152
	v_mul_f32_e32 v153, v43, v153
	v_fma_f32 v150, v40, v150, v40
	v_fma_f32 v151, v41, v151, v41
	v_fma_f32 v152, v42, v152, v42
	v_fma_f32 v153, v43, v153, v43
	v_mul_f32_e32 v150, 0x3f4c422a, v150
	v_mul_f32_e32 v151, 0x3f4c422a, v151
	v_mul_f32_e32 v152, 0x3f4c422a, v152
	v_mul_f32_e32 v153, 0x3f4c422a, v153
	v_add_f32_e32 v150, v150, v150
	v_add_f32_e32 v151, v151, v151
	v_add_f32_e32 v152, v152, v152
	v_add_f32_e32 v153, v153, v153
	v_mul_f32_e32 v150, 0x3fb8aa3b, v150
	v_mul_f32_e32 v151, 0x3fb8aa3b, v151
	v_mul_f32_e32 v152, 0x3fb8aa3b, v152
	v_mul_f32_e32 v153, 0x3fb8aa3b, v153
	v_exp_f32_e32 v150, v150
	v_exp_f32_e32 v151, v151
	v_exp_f32_e32 v152, v152
	v_exp_f32_e32 v153, v153
	v_add_f32_e32 v150, 1.0, v150
	v_add_f32_e32 v151, 1.0, v151
	v_add_f32_e32 v152, 1.0, v152
	v_add_f32_e32 v153, 1.0, v153
	v_rcp_f32_e32 v150, v150
	v_rcp_f32_e32 v151, v151
	v_rcp_f32_e32 v152, v152
	v_rcp_f32_e32 v153, v153
	v_pk_mul_f32 v[40:41], v[40:41], 0.5 op_sel_hi:[1,0]
	v_pk_mul_f32 v[42:43], v[42:43], 0.5 op_sel_hi:[1,0]
	v_pk_fma_f32 v[150:151], v[150:151], 2.0, 1.0 op_sel_hi:[1,0,0] neg_lo:[1,0,0] neg_hi:[1,0,0]
	v_pk_fma_f32 v[152:153], v[152:153], 2.0, 1.0 op_sel_hi:[1,0,0] neg_lo:[1,0,0] neg_hi:[1,0,0]
	v_pk_add_f32 v[150:151], v[150:151], 1.0 op_sel_hi:[1,0]
	v_pk_add_f32 v[152:153], v[152:153], 1.0 op_sel_hi:[1,0]
	v_pk_mul_f32 v[40:41], v[40:41], v[150:151]
	v_pk_mul_f32 v[42:43], v[42:43], v[152:153]
	s_nop 0
	v_cvt_pk_bf16_f32 v40, v40, v41
	v_cvt_pk_bf16_f32 v41, v42, v43
	global_store_dwordx2 v141, v[40:41], s[78:79]
	s_waitcnt vmcnt(23)
	v_lshlrev_b32_e32 v150, 16, v118
	v_and_b32_e32 v151, 0xffff0000, v118
	v_lshlrev_b32_e32 v152, 16, v119
	v_and_b32_e32 v153, 0xffff0000, v119
	v_or_b32_e32 v139, s22, v136
	v_pk_fma_f32 v[36:37], v[154:155], v[150:151], v[36:37]
	v_pk_fma_f32 v[38:39], v[156:157], v[152:153], v[38:39]
	v_or_b32_e32 v139, s6, v139
	v_lshl_add_u32 v141, v139, 10, v146
	v_mul_f32_e32 v150, 0x3d372713, v36
	v_mul_f32_e32 v151, 0x3d372713, v37
	v_mul_f32_e32 v152, 0x3d372713, v38
	v_mul_f32_e32 v153, 0x3d372713, v39
	v_mul_f32_e32 v150, v36, v150
	v_mul_f32_e32 v151, v37, v151
	v_mul_f32_e32 v152, v38, v152
	v_mul_f32_e32 v153, v39, v153
	v_fma_f32 v150, v36, v150, v36
	v_fma_f32 v151, v37, v151, v37
	v_fma_f32 v152, v38, v152, v38
	v_fma_f32 v153, v39, v153, v39
	v_mul_f32_e32 v150, 0x3f4c422a, v150
	v_mul_f32_e32 v151, 0x3f4c422a, v151
	v_mul_f32_e32 v152, 0x3f4c422a, v152
	v_mul_f32_e32 v153, 0x3f4c422a, v153
	v_add_f32_e32 v150, v150, v150
	v_add_f32_e32 v151, v151, v151
	v_add_f32_e32 v152, v152, v152
	v_add_f32_e32 v153, v153, v153
	v_mul_f32_e32 v150, 0x3fb8aa3b, v150
	v_mul_f32_e32 v151, 0x3fb8aa3b, v151
	v_mul_f32_e32 v152, 0x3fb8aa3b, v152
	v_mul_f32_e32 v153, 0x3fb8aa3b, v153
	v_exp_f32_e32 v150, v150
	v_exp_f32_e32 v151, v151
	v_exp_f32_e32 v152, v152
	v_exp_f32_e32 v153, v153
	v_add_f32_e32 v150, 1.0, v150
	v_add_f32_e32 v151, 1.0, v151
	v_add_f32_e32 v152, 1.0, v152
	v_add_f32_e32 v153, 1.0, v153
	v_rcp_f32_e32 v150, v150
	v_rcp_f32_e32 v151, v151
	v_rcp_f32_e32 v152, v152
	v_rcp_f32_e32 v153, v153
	v_pk_mul_f32 v[36:37], v[36:37], 0.5 op_sel_hi:[1,0]
	v_pk_mul_f32 v[38:39], v[38:39], 0.5 op_sel_hi:[1,0]
	v_pk_fma_f32 v[150:151], v[150:151], 2.0, 1.0 op_sel_hi:[1,0,0] neg_lo:[1,0,0] neg_hi:[1,0,0]
	v_pk_fma_f32 v[152:153], v[152:153], 2.0, 1.0 op_sel_hi:[1,0,0] neg_lo:[1,0,0] neg_hi:[1,0,0]
	v_pk_add_f32 v[150:151], v[150:151], 1.0 op_sel_hi:[1,0]
	v_pk_add_f32 v[152:153], v[152:153], 1.0 op_sel_hi:[1,0]
	v_pk_mul_f32 v[36:37], v[36:37], v[150:151]
	v_pk_mul_f32 v[38:39], v[38:39], v[152:153]
	s_nop 0
	v_cvt_pk_bf16_f32 v36, v36, v37
	v_cvt_pk_bf16_f32 v37, v38, v39
	global_store_dwordx2 v141, v[36:37], s[78:79]
	s_waitcnt vmcnt(23)
; __device__ __forceinline__ float bflo(unsigned w) { return __uint_as_float(w << 16); }
; __device__ __forceinline__ float bfhi(unsigned w) { return __uint_as_float(w & 0xffff0000u); }
; __device__ __forceinline__ unsigned pk2(float lo, float hi) { return pg8::cvt_pk_bf16(lo, hi); }
; __device__ __forceinline__ float gelu_tanh(float y) { const float a = 0.7978845608028654f * (y + 0.044715f * y * y * y); const float e = __expf(2.0f * a); const float th = 1.0f - 2.0f * __builtin_amdgcn_rcpf(e + 1.0f); return 0.5f * y * (1.0f + th); }
;     __device__ __forceinline__ void operator()(const f32x4 (&acc)[2][2][4][2], const Unit& u, int wr, int wc, int fr, int fq) const {
;     ...
;             for (int m = 0; m < 4; ++m) { const int rowg = mh * 256 + ai * 128 + wr * 64 + m * 16 + fr, b = rowg >> 6, c = rowg & 63;
; #pragma unroll
;                 for (int bj = 0; bj < 2; ++bj)
; #pragma unroll
;                     for (int n = 0; n < 2; ++n) { const int colg = nh * 256 + bj * 128 + wc * 32 + n * 16 + 4 * fq, tau = colg >> 4, ch = g * 16 + (colg & 15);
;                         const size_t tok = (size_t)b * SEQ + 32 * c + tau;
;                         const u32x2 uw = *(const u32x2*)(z + tok * ZP + C_SU + ch); const f32x4 d4 = *(const f32x4*)(dsk + ch); const f32x4 a = acc[ai][bj][m][n];
;                         u32x2 o; o.x = pk2(gelu_tanh(a[0] + d4[0] * bflo(uw.x)), gelu_tanh(a[1] + d4[1] * bfhi(uw.x))); o.y = pk2(gelu_tanh(a[2] + d4[2] * bflo(uw.y)), gelu_tanh(a[3] + d4[3] * bfhi(uw.y)));
;                         *(u32x2*)(ysg + tok * 512 + ch) = o; } }
	v_lshlrev_b32_e32 v150, 16, v112
	v_and_b32_e32 v151, 0xffff0000, v112
	v_lshlrev_b32_e32 v152, 16, v113
	v_and_b32_e32 v153, 0xffff0000, v113
	v_or_b32_e32 v139, s22, v138
	v_pk_fma_f32 v[32:33], v[154:155], v[150:151], v[32:33]
	v_pk_fma_f32 v[34:35], v[156:157], v[152:153], v[34:35]
	v_or_b32_e32 v139, s7, v139
	v_lshl_add_u32 v141, v139, 10, v146
	v_mul_f32_e32 v150, 0x3d372713, v32
	v_mul_f32_e32 v151, 0x3d372713, v33
	v_mul_f32_e32 v152, 0x3d372713, v34
	v_mul_f32_e32 v153, 0x3d372713, v35
	v_mul_f32_e32 v150, v32, v150
	v_mul_f32_e32 v151, v33, v151
	v_mul_f32_e32 v152, v34, v152
	v_mul_f32_e32 v153, v35, v153
	v_fma_f32 v150, v32, v150, v32
	v_fma_f32 v151, v33, v151, v33
	v_fma_f32 v152, v34, v152, v34
	v_fma_f32 v153, v35, v153, v35
	v_mul_f32_e32 v150, 0x3f4c422a, v150
	v_mul_f32_e32 v151, 0x3f4c422a, v151
	v_mul_f32_e32 v152, 0x3f4c422a, v152
	v_mul_f32_e32 v153, 0x3f4c422a, v153
	v_add_f32_e32 v150, v150, v150
	v_add_f32_e32 v151, v151, v151
	v_add_f32_e32 v152, v152, v152
	v_add_f32_e32 v153, v153, v153
	v_mul_f32_e32 v150, 0x3fb8aa3b, v150
	v_mul_f32_e32 v151, 0x3fb8aa3b, v151
	v_mul_f32_e32 v152, 0x3fb8aa3b, v152
	v_mul_f32_e32 v153, 0x3fb8aa3b, v153
	v_exp_f32_e32 v150, v150
	v_exp_f32_e32 v151, v151
	v_exp_f32_e32 v152, v152
	v_exp_f32_e32 v153, v153
	v_add_f32_e32 v150, 1.0, v150
	v_add_f32_e32 v151, 1.0, v151
	v_add_f32_e32 v152, 1.0, v152
	v_add_f32_e32 v153, 1.0, v153
	v_rcp_f32_e32 v150, v150
	v_rcp_f32_e32 v151, v151
	v_rcp_f32_e32 v152, v152
	v_rcp_f32_e32 v153, v153
	v_pk_mul_f32 v[32:33], v[32:33], 0.5 op_sel_hi:[1,0]
	v_pk_mul_f32 v[34:35], v[34:35], 0.5 op_sel_hi:[1,0]
	v_pk_fma_f32 v[150:151], v[150:151], 2.0, 1.0 op_sel_hi:[1,0,0] neg_lo:[1,0,0] neg_hi:[1,0,0]
	v_pk_fma_f32 v[152:153], v[152:153], 2.0, 1.0 op_sel_hi:[1,0,0] neg_lo:[1,0,0] neg_hi:[1,0,0]
	v_pk_add_f32 v[150:151], v[150:151], 1.0 op_sel_hi:[1,0]
	v_pk_add_f32 v[152:153], v[152:153], 1.0 op_sel_hi:[1,0]
	v_pk_mul_f32 v[32:33], v[32:33], v[150:151]
	v_pk_mul_f32 v[34:35], v[34:35], v[152:153]
	s_nop 0
	v_cvt_pk_bf16_f32 v32, v32, v33
	v_cvt_pk_bf16_f32 v33, v34, v35
	global_store_dwordx2 v141, v[32:33], s[78:79]
	s_waitcnt vmcnt(23)
	v_lshlrev_b32_e32 v150, 16, v114
	v_and_b32_e32 v151, 0xffff0000, v114
	v_lshlrev_b32_e32 v152, 16, v115
	v_and_b32_e32 v153, 0xffff0000, v115
	v_or_b32_e32 v139, s22, v138
	v_pk_fma_f32 v[28:29], v[154:155], v[150:151], v[28:29]
	v_pk_fma_f32 v[30:31], v[156:157], v[152:153], v[30:31]
	v_or_b32_e32 v139, s5, v139
	v_lshl_add_u32 v141, v139, 10, v146
	v_mul_f32_e32 v150, 0x3d372713, v28
	v_mul_f32_e32 v151, 0x3d372713, v29
	v_mul_f32_e32 v152, 0x3d372713, v30
	v_mul_f32_e32 v153, 0x3d372713, v31
	v_mul_f32_e32 v150, v28, v150
	v_mul_f32_e32 v151, v29, v151
	v_mul_f32_e32 v152, v30, v152
	v_mul_f32_e32 v153, v31, v153
	v_fma_f32 v150, v28, v150, v28
	v_fma_f32 v151, v29, v151, v29
	v_fma_f32 v152, v30, v152, v30
	v_fma_f32 v153, v31, v153, v31
	v_mul_f32_e32 v150, 0x3f4c422a, v150
	v_mul_f32_e32 v151, 0x3f4c422a, v151
	v_mul_f32_e32 v152, 0x3f4c422a, v152
	v_mul_f32_e32 v153, 0x3f4c422a, v153
	v_add_f32_e32 v150, v150, v150
	v_add_f32_e32 v151, v151, v151
	v_add_f32_e32 v152, v152, v152
	v_add_f32_e32 v153, v153, v153
	v_mul_f32_e32 v150, 0x3fb8aa3b, v150
	v_mul_f32_e32 v151, 0x3fb8aa3b, v151
	v_mul_f32_e32 v152, 0x3fb8aa3b, v152
	v_mul_f32_e32 v153, 0x3fb8aa3b, v153
	v_exp_f32_e32 v150, v150
	v_exp_f32_e32 v151, v151
	v_exp_f32_e32 v152, v152
	v_exp_f32_e32 v153, v153
	v_add_f32_e32 v150, 1.0, v150
	v_add_f32_e32 v151, 1.0, v151
	v_add_f32_e32 v152, 1.0, v152
	v_add_f32_e32 v153, 1.0, v153
	v_rcp_f32_e32 v150, v150
	v_rcp_f32_e32 v151, v151
	v_rcp_f32_e32 v152, v152
	v_rcp_f32_e32 v153, v153
	v_pk_mul_f32 v[28:29], v[28:29], 0.5 op_sel_hi:[1,0]
	v_pk_mul_f32 v[30:31], v[30:31], 0.5 op_sel_hi:[1,0]
	v_pk_fma_f32 v[150:151], v[150:151], 2.0, 1.0 op_sel_hi:[1,0,0] neg_lo:[1,0,0] neg_hi:[1,0,0]
	v_pk_fma_f32 v[152:153], v[152:153], 2.0, 1.0 op_sel_hi:[1,0,0] neg_lo:[1,0,0] neg_hi:[1,0,0]
	v_pk_add_f32 v[150:151], v[150:151], 1.0 op_sel_hi:[1,0]
	v_pk_add_f32 v[152:153], v[152:153], 1.0 op_sel_hi:[1,0]
	v_pk_mul_f32 v[28:29], v[28:29], v[150:151]
	v_pk_mul_f32 v[30:31], v[30:31], v[152:153]
	s_nop 0
	v_cvt_pk_bf16_f32 v28, v28, v29
	v_cvt_pk_bf16_f32 v29, v30, v31
	global_store_dwordx2 v141, v[28:29], s[78:79]
	s_waitcnt vmcnt(23)
	v_lshlrev_b32_e32 v150, 16, v108
	v_and_b32_e32 v151, 0xffff0000, v108
	v_lshlrev_b32_e32 v152, 16, v109
	v_and_b32_e32 v153, 0xffff0000, v109
	v_or_b32_e32 v139, s22, v138
	v_pk_fma_f32 v[24:25], v[154:155], v[150:151], v[24:25]
	v_pk_fma_f32 v[26:27], v[156:157], v[152:153], v[26:27]
	v_or_b32_e32 v139, s4, v139
	v_lshl_add_u32 v141, v139, 10, v146
	v_mul_f32_e32 v150, 0x3d372713, v24
	v_mul_f32_e32 v151, 0x3d372713, v25
	v_mul_f32_e32 v152, 0x3d372713, v26
	v_mul_f32_e32 v153, 0x3d372713, v27
	v_mul_f32_e32 v150, v24, v150
	v_mul_f32_e32 v151, v25, v151
	v_mul_f32_e32 v152, v26, v152
	v_mul_f32_e32 v153, v27, v153
	v_fma_f32 v150, v24, v150, v24
	v_fma_f32 v151, v25, v151, v25
	v_fma_f32 v152, v26, v152, v26
	v_fma_f32 v153, v27, v153, v27
	v_mul_f32_e32 v150, 0x3f4c422a, v150
	v_mul_f32_e32 v151, 0x3f4c422a, v151
	v_mul_f32_e32 v152, 0x3f4c422a, v152
	v_mul_f32_e32 v153, 0x3f4c422a, v153
	v_add_f32_e32 v150, v150, v150
	v_add_f32_e32 v151, v151, v151
	v_add_f32_e32 v152, v152, v152
	v_add_f32_e32 v153, v153, v153
	v_mul_f32_e32 v150, 0x3fb8aa3b, v150
	v_mul_f32_e32 v151, 0x3fb8aa3b, v151
	v_mul_f32_e32 v152, 0x3fb8aa3b, v152
	v_mul_f32_e32 v153, 0x3fb8aa3b, v153
	v_exp_f32_e32 v150, v150
	v_exp_f32_e32 v151, v151
	v_exp_f32_e32 v152, v152
	v_exp_f32_e32 v153, v153
	v_add_f32_e32 v150, 1.0, v150
	v_add_f32_e32 v151, 1.0, v151
	v_add_f32_e32 v152, 1.0, v152
	v_add_f32_e32 v153, 1.0, v153
	v_rcp_f32_e32 v150, v150
	v_rcp_f32_e32 v151, v151
	v_rcp_f32_e32 v152, v152
	v_rcp_f32_e32 v153, v153
	v_pk_mul_f32 v[24:25], v[24:25], 0.5 op_sel_hi:[1,0]
	v_pk_mul_f32 v[26:27], v[26:27], 0.5 op_sel_hi:[1,0]
	v_pk_fma_f32 v[150:151], v[150:151], 2.0, 1.0 op_sel_hi:[1,0,0] neg_lo:[1,0,0] neg_hi:[1,0,0]
	v_pk_fma_f32 v[152:153], v[152:153], 2.0, 1.0 op_sel_hi:[1,0,0] neg_lo:[1,0,0] neg_hi:[1,0,0]
	v_pk_add_f32 v[150:151], v[150:151], 1.0 op_sel_hi:[1,0]
	v_pk_add_f32 v[152:153], v[152:153], 1.0 op_sel_hi:[1,0]
	v_pk_mul_f32 v[24:25], v[24:25], v[150:151]
	v_pk_mul_f32 v[26:27], v[26:27], v[152:153]
	s_nop 0
	v_cvt_pk_bf16_f32 v24, v24, v25
	v_cvt_pk_bf16_f32 v25, v26, v27
	global_store_dwordx2 v141, v[24:25], s[78:79]
	s_waitcnt vmcnt(23)
; __device__ __forceinline__ float bflo(unsigned w) { return __uint_as_float(w << 16); }
; __device__ __forceinline__ float bfhi(unsigned w) { return __uint_as_float(w & 0xffff0000u); }
; __device__ __forceinline__ unsigned pk2(float lo, float hi) { return pg8::cvt_pk_bf16(lo, hi); }
; __device__ __forceinline__ float gelu_tanh(float y) { const float a = 0.7978845608028654f * (y + 0.044715f * y * y * y); const float e = __expf(2.0f * a); const float th = 1.0f - 2.0f * __builtin_amdgcn_rcpf(e + 1.0f); return 0.5f * y * (1.0f + th); }
;     __device__ __forceinline__ void operator()(const f32x4 (&acc)[2][2][4][2], const Unit& u, int wr, int wc, int fr, int fq) const {
;     ...
;             for (int m = 0; m < 4; ++m) { const int rowg = mh * 256 + ai * 128 + wr * 64 + m * 16 + fr, b = rowg >> 6, c = rowg & 63;
; #pragma unroll
;                 for (int bj = 0; bj < 2; ++bj)
; #pragma unroll
;                     for (int n = 0; n < 2; ++n) { const int colg = nh * 256 + bj * 128 + wc * 32 + n * 16 + 4 * fq, tau = colg >> 4, ch = g * 16 + (colg & 15);
;                         const size_t tok = (size_t)b * SEQ + 32 * c + tau;
;                         const u32x2 uw = *(const u32x2*)(z + tok * ZP + C_SU + ch); const f32x4 d4 = *(const f32x4*)(dsk + ch); const f32x4 a = acc[ai][bj][m][n];
;                         u32x2 o; o.x = pk2(gelu_tanh(a[0] + d4[0] * bflo(uw.x)), gelu_tanh(a[1] + d4[1] * bfhi(uw.x))); o.y = pk2(gelu_tanh(a[2] + d4[2] * bflo(uw.y)), gelu_tanh(a[3] + d4[3] * bfhi(uw.y)));
;                         *(u32x2*)(ysg + tok * 512 + ch) = o; } }
	v_lshlrev_b32_e32 v150, 16, v110
	v_and_b32_e32 v151, 0xffff0000, v110
	v_lshlrev_b32_e32 v152, 16, v111
	v_and_b32_e32 v153, 0xffff0000, v111
	v_or_b32_e32 v139, s22, v138
	v_pk_fma_f32 v[20:21], v[154:155], v[150:151], v[20:21]
	v_pk_fma_f32 v[22:23], v[156:157], v[152:153], v[22:23]
	v_or_b32_e32 v139, s6, v139
	v_lshl_add_u32 v141, v139, 10, v146
	v_mul_f32_e32 v150, 0x3d372713, v20
	v_mul_f32_e32 v151, 0x3d372713, v21
	v_mul_f32_e32 v152, 0x3d372713, v22
	v_mul_f32_e32 v153, 0x3d372713, v23
	v_mul_f32_e32 v150, v20, v150
	v_mul_f32_e32 v151, v21, v151
	v_mul_f32_e32 v152, v22, v152
	v_mul_f32_e32 v153, v23, v153
	v_fma_f32 v150, v20, v150, v20
	v_fma_f32 v151, v21, v151, v21
	v_fma_f32 v152, v22, v152, v22
	v_fma_f32 v153, v23, v153, v23
	v_mul_f32_e32 v150, 0x3f4c422a, v150
	v_mul_f32_e32 v151, 0x3f4c422a, v151
	v_mul_f32_e32 v152, 0x3f4c422a, v152
	v_mul_f32_e32 v153, 0x3f4c422a, v153
	v_add_f32_e32 v150, v150, v150
	v_add_f32_e32 v151, v151, v151
	v_add_f32_e32 v152, v152, v152
	v_add_f32_e32 v153, v153, v153
	v_mul_f32_e32 v150, 0x3fb8aa3b, v150
	v_mul_f32_e32 v151, 0x3fb8aa3b, v151
	v_mul_f32_e32 v152, 0x3fb8aa3b, v152
	v_mul_f32_e32 v153, 0x3fb8aa3b, v153
	v_exp_f32_e32 v150, v150
	v_exp_f32_e32 v151, v151
	v_exp_f32_e32 v152, v152
	v_exp_f32_e32 v153, v153
	v_add_f32_e32 v150, 1.0, v150
	v_add_f32_e32 v151, 1.0, v151
	v_add_f32_e32 v152, 1.0, v152
	v_add_f32_e32 v153, 1.0, v153
	v_rcp_f32_e32 v150, v150
	v_rcp_f32_e32 v151, v151
	v_rcp_f32_e32 v152, v152
	v_rcp_f32_e32 v153, v153
	v_pk_mul_f32 v[20:21], v[20:21], 0.5 op_sel_hi:[1,0]
	v_pk_mul_f32 v[22:23], v[22:23], 0.5 op_sel_hi:[1,0]
	v_pk_fma_f32 v[150:151], v[150:151], 2.0, 1.0 op_sel_hi:[1,0,0] neg_lo:[1,0,0] neg_hi:[1,0,0]
	v_pk_fma_f32 v[152:153], v[152:153], 2.0, 1.0 op_sel_hi:[1,0,0] neg_lo:[1,0,0] neg_hi:[1,0,0]
	v_pk_add_f32 v[150:151], v[150:151], 1.0 op_sel_hi:[1,0]
	v_pk_add_f32 v[152:153], v[152:153], 1.0 op_sel_hi:[1,0]
	v_pk_mul_f32 v[20:21], v[20:21], v[150:151]
	v_pk_mul_f32 v[22:23], v[22:23], v[152:153]
	s_nop 0
	v_cvt_pk_bf16_f32 v20, v20, v21
	v_cvt_pk_bf16_f32 v21, v22, v23
	global_store_dwordx2 v141, v[20:21], s[78:79]
	s_waitcnt vmcnt(23)
	v_lshlrev_b32_e32 v150, 16, v104
	v_and_b32_e32 v151, 0xffff0000, v104
	v_lshlrev_b32_e32 v152, 16, v105
	v_and_b32_e32 v153, 0xffff0000, v105
	v_or_b32_e32 v139, s22, v140
	v_pk_fma_f32 v[16:17], v[154:155], v[150:151], v[16:17]
	v_pk_fma_f32 v[18:19], v[156:157], v[152:153], v[18:19]
	v_or_b32_e32 v139, s7, v139
	v_lshl_add_u32 v141, v139, 10, v146
	v_mul_f32_e32 v150, 0x3d372713, v16
	v_mul_f32_e32 v151, 0x3d372713, v17
	v_mul_f32_e32 v152, 0x3d372713, v18
	v_mul_f32_e32 v153, 0x3d372713, v19
	v_mul_f32_e32 v150, v16, v150
	v_mul_f32_e32 v151, v17, v151
	v_mul_f32_e32 v152, v18, v152
	v_mul_f32_e32 v153, v19, v153
	v_fma_f32 v150, v16, v150, v16
	v_fma_f32 v151, v17, v151, v17
	v_fma_f32 v152, v18, v152, v18
	v_fma_f32 v153, v19, v153, v19
	v_mul_f32_e32 v150, 0x3f4c422a, v150
	v_mul_f32_e32 v151, 0x3f4c422a, v151
	v_mul_f32_e32 v152, 0x3f4c422a, v152
	v_mul_f32_e32 v153, 0x3f4c422a, v153
	v_add_f32_e32 v150, v150, v150
	v_add_f32_e32 v151, v151, v151
	v_add_f32_e32 v152, v152, v152
	v_add_f32_e32 v153, v153, v153
	v_mul_f32_e32 v150, 0x3fb8aa3b, v150
	v_mul_f32_e32 v151, 0x3fb8aa3b, v151
	v_mul_f32_e32 v152, 0x3fb8aa3b, v152
	v_mul_f32_e32 v153, 0x3fb8aa3b, v153
	v_exp_f32_e32 v150, v150
	v_exp_f32_e32 v151, v151
	v_exp_f32_e32 v152, v152
	v_exp_f32_e32 v153, v153
	v_add_f32_e32 v150, 1.0, v150
	v_add_f32_e32 v151, 1.0, v151
	v_add_f32_e32 v152, 1.0, v152
	v_add_f32_e32 v153, 1.0, v153
	v_rcp_f32_e32 v150, v150
	v_rcp_f32_e32 v151, v151
	v_rcp_f32_e32 v152, v152
	v_rcp_f32_e32 v153, v153
	v_pk_mul_f32 v[16:17], v[16:17], 0.5 op_sel_hi:[1,0]
	v_pk_mul_f32 v[18:19], v[18:19], 0.5 op_sel_hi:[1,0]
	v_pk_fma_f32 v[150:151], v[150:151], 2.0, 1.0 op_sel_hi:[1,0,0] neg_lo:[1,0,0] neg_hi:[1,0,0]
	v_pk_fma_f32 v[152:153], v[152:153], 2.0, 1.0 op_sel_hi:[1,0,0] neg_lo:[1,0,0] neg_hi:[1,0,0]
	v_pk_add_f32 v[150:151], v[150:151], 1.0 op_sel_hi:[1,0]
	v_pk_add_f32 v[152:153], v[152:153], 1.0 op_sel_hi:[1,0]
	v_pk_mul_f32 v[16:17], v[16:17], v[150:151]
	v_pk_mul_f32 v[18:19], v[18:19], v[152:153]
	s_nop 0
	v_cvt_pk_bf16_f32 v16, v16, v17
	v_cvt_pk_bf16_f32 v17, v18, v19
	global_store_dwordx2 v141, v[16:17], s[78:79]
	s_waitcnt vmcnt(23)
	v_lshlrev_b32_e32 v150, 16, v106
	v_and_b32_e32 v151, 0xffff0000, v106
	v_lshlrev_b32_e32 v152, 16, v107
	v_and_b32_e32 v153, 0xffff0000, v107
	v_or_b32_e32 v139, s22, v140
	v_pk_fma_f32 v[12:13], v[154:155], v[150:151], v[12:13]
	v_pk_fma_f32 v[14:15], v[156:157], v[152:153], v[14:15]
	v_or_b32_e32 v139, s5, v139
	v_lshl_add_u32 v141, v139, 10, v146
	v_mul_f32_e32 v150, 0x3d372713, v12
	v_mul_f32_e32 v151, 0x3d372713, v13
	v_mul_f32_e32 v152, 0x3d372713, v14
	v_mul_f32_e32 v153, 0x3d372713, v15
	v_mul_f32_e32 v150, v12, v150
	v_mul_f32_e32 v151, v13, v151
	v_mul_f32_e32 v152, v14, v152
	v_mul_f32_e32 v153, v15, v153
	v_fma_f32 v150, v12, v150, v12
	v_fma_f32 v151, v13, v151, v13
	v_fma_f32 v152, v14, v152, v14
	v_fma_f32 v153, v15, v153, v15
	v_mul_f32_e32 v150, 0x3f4c422a, v150
	v_mul_f32_e32 v151, 0x3f4c422a, v151
	v_mul_f32_e32 v152, 0x3f4c422a, v152
	v_mul_f32_e32 v153, 0x3f4c422a, v153
	v_add_f32_e32 v150, v150, v150
	v_add_f32_e32 v151, v151, v151
	v_add_f32_e32 v152, v152, v152
	v_add_f32_e32 v153, v153, v153
	v_mul_f32_e32 v150, 0x3fb8aa3b, v150
	v_mul_f32_e32 v151, 0x3fb8aa3b, v151
	v_mul_f32_e32 v152, 0x3fb8aa3b, v152
	v_mul_f32_e32 v153, 0x3fb8aa3b, v153
	v_exp_f32_e32 v150, v150
	v_exp_f32_e32 v151, v151
	v_exp_f32_e32 v152, v152
	v_exp_f32_e32 v153, v153
	v_add_f32_e32 v150, 1.0, v150
	v_add_f32_e32 v151, 1.0, v151
	v_add_f32_e32 v152, 1.0, v152
	v_add_f32_e32 v153, 1.0, v153
	v_rcp_f32_e32 v150, v150
	v_rcp_f32_e32 v151, v151
	v_rcp_f32_e32 v152, v152
	v_rcp_f32_e32 v153, v153
	v_pk_mul_f32 v[12:13], v[12:13], 0.5 op_sel_hi:[1,0]
	v_pk_mul_f32 v[14:15], v[14:15], 0.5 op_sel_hi:[1,0]
	v_pk_fma_f32 v[150:151], v[150:151], 2.0, 1.0 op_sel_hi:[1,0,0] neg_lo:[1,0,0] neg_hi:[1,0,0]
	v_pk_fma_f32 v[152:153], v[152:153], 2.0, 1.0 op_sel_hi:[1,0,0] neg_lo:[1,0,0] neg_hi:[1,0,0]
	v_pk_add_f32 v[150:151], v[150:151], 1.0 op_sel_hi:[1,0]
	v_pk_add_f32 v[152:153], v[152:153], 1.0 op_sel_hi:[1,0]
	v_pk_mul_f32 v[12:13], v[12:13], v[150:151]
	v_pk_mul_f32 v[14:15], v[14:15], v[152:153]
	s_nop 0
	v_cvt_pk_bf16_f32 v12, v12, v13
	v_cvt_pk_bf16_f32 v13, v14, v15
	global_store_dwordx2 v141, v[12:13], s[78:79]
	s_waitcnt vmcnt(23)
; #define PG8_BAR __builtin_amdgcn_s_barrier()
; __device__ __forceinline__ float bflo(unsigned w) { return __uint_as_float(w << 16); }
; __device__ __forceinline__ float bfhi(unsigned w) { return __uint_as_float(w & 0xffff0000u); }
; __device__ __forceinline__ unsigned pk2(float lo, float hi) { return pg8::cvt_pk_bf16(lo, hi); }
; __device__ __forceinline__ float gelu_tanh(float y) { const float a = 0.7978845608028654f * (y + 0.044715f * y * y * y); const float e = __expf(2.0f * a); const float th = 1.0f - 2.0f * __builtin_amdgcn_rcpf(e + 1.0f); return 0.5f * y * (1.0f + th); }
; template <class Epi, class Sched, bool ALIGN_EPI = false, bool SP2 = false>
; __device__ __forceinline__ void gemm_phase(PG8_LAS unsigned char* lds, const Gemm g, const Sched& S, const Epi& E) {
;     ...
;         if (!has_next) break;
; #pragma unroll
;         for (int a = 0; a < 2; ++a)
; #pragma unroll
;             for (int b = 0; b < 2; ++b)
; #pragma unroll
;                 for (int m = 0; m < 4; ++m)
; #pragma unroll
;                     for (int n = 0; n < 2; ++n) acc[a][b][m][n] = (f32x4){0.f, 0.f, 0.f, 0.f};
;         cur = nxt; cA = nA; cB = nB; ++ui;
;         if constexpr (ALIGN_EPI) { if (wr == 1) PG8_BAR; }
;     __device__ __forceinline__ void operator()(const f32x4 (&acc)[2][2][4][2], const Unit& u, int wr, int wc, int fr, int fq) const {
;     ...
;             for (int m = 0; m < 4; ++m) { const int rowg = mh * 256 + ai * 128 + wr * 64 + m * 16 + fr, b = rowg >> 6, c = rowg & 63;
; #pragma unroll
;                 for (int bj = 0; bj < 2; ++bj)
; #pragma unroll
;                     for (int n = 0; n < 2; ++n) { const int colg = nh * 256 + bj * 128 + wc * 32 + n * 16 + 4 * fq, tau = colg >> 4, ch = g * 16 + (colg & 15);
;                         const size_t tok = (size_t)b * SEQ + 32 * c + tau;
;                         const u32x2 uw = *(const u32x2*)(z + tok * ZP + C_SU + ch); const f32x4 d4 = *(const f32x4*)(dsk + ch); const f32x4 a = acc[ai][bj][m][n];
;                         u32x2 o; o.x = pk2(gelu_tanh(a[0] + d4[0] * bflo(uw.x)), gelu_tanh(a[1] + d4[1] * bfhi(uw.x))); o.y = pk2(gelu_tanh(a[2] + d4[2] * bflo(uw.y)), gelu_tanh(a[3] + d4[3] * bfhi(uw.y)));
;                         *(u32x2*)(ysg + tok * 512 + ch) = o; } }
	v_lshlrev_b32_e32 v150, 16, v100
	v_and_b32_e32 v151, 0xffff0000, v100
	v_lshlrev_b32_e32 v152, 16, v101
	v_and_b32_e32 v153, 0xffff0000, v101
	v_or_b32_e32 v139, s22, v140
	v_pk_fma_f32 v[8:9], v[154:155], v[150:151], v[8:9]
	v_pk_fma_f32 v[10:11], v[156:157], v[152:153], v[10:11]
	v_or_b32_e32 v139, s4, v139
	v_lshl_add_u32 v141, v139, 10, v146
	v_mul_f32_e32 v150, 0x3d372713, v8
	v_mul_f32_e32 v151, 0x3d372713, v9
	v_mul_f32_e32 v152, 0x3d372713, v10
	v_mul_f32_e32 v153, 0x3d372713, v11
	v_mul_f32_e32 v150, v8, v150
	v_mul_f32_e32 v151, v9, v151
	v_mul_f32_e32 v152, v10, v152
	v_mul_f32_e32 v153, v11, v153
	v_fma_f32 v150, v8, v150, v8
	v_fma_f32 v151, v9, v151, v9
	v_fma_f32 v152, v10, v152, v10
	v_fma_f32 v153, v11, v153, v11
	v_mul_f32_e32 v150, 0x3f4c422a, v150
	v_mul_f32_e32 v151, 0x3f4c422a, v151
	v_mul_f32_e32 v152, 0x3f4c422a, v152
	v_mul_f32_e32 v153, 0x3f4c422a, v153
	v_add_f32_e32 v150, v150, v150
	v_add_f32_e32 v151, v151, v151
	v_add_f32_e32 v152, v152, v152
	v_add_f32_e32 v153, v153, v153
	v_mul_f32_e32 v150, 0x3fb8aa3b, v150
	v_mul_f32_e32 v151, 0x3fb8aa3b, v151
	v_mul_f32_e32 v152, 0x3fb8aa3b, v152
	v_mul_f32_e32 v153, 0x3fb8aa3b, v153
	v_exp_f32_e32 v150, v150
	v_exp_f32_e32 v151, v151
	v_exp_f32_e32 v152, v152
	v_exp_f32_e32 v153, v153
	v_add_f32_e32 v150, 1.0, v150
	v_add_f32_e32 v151, 1.0, v151
	v_add_f32_e32 v152, 1.0, v152
	v_add_f32_e32 v153, 1.0, v153
	v_rcp_f32_e32 v150, v150
	v_rcp_f32_e32 v151, v151
	v_rcp_f32_e32 v152, v152
	v_rcp_f32_e32 v153, v153
	v_pk_mul_f32 v[8:9], v[8:9], 0.5 op_sel_hi:[1,0]
	v_pk_mul_f32 v[10:11], v[10:11], 0.5 op_sel_hi:[1,0]
	v_pk_fma_f32 v[150:151], v[150:151], 2.0, 1.0 op_sel_hi:[1,0,0] neg_lo:[1,0,0] neg_hi:[1,0,0]
	v_pk_fma_f32 v[152:153], v[152:153], 2.0, 1.0 op_sel_hi:[1,0,0] neg_lo:[1,0,0] neg_hi:[1,0,0]
	v_pk_add_f32 v[150:151], v[150:151], 1.0 op_sel_hi:[1,0]
	v_pk_add_f32 v[152:153], v[152:153], 1.0 op_sel_hi:[1,0]
	v_pk_mul_f32 v[8:9], v[8:9], v[150:151]
	v_pk_mul_f32 v[10:11], v[10:11], v[152:153]
	s_nop 0
	v_cvt_pk_bf16_f32 v8, v8, v9
	v_cvt_pk_bf16_f32 v9, v10, v11
	global_store_dwordx2 v141, v[8:9], s[78:79]
	s_waitcnt vmcnt(23)
	v_lshlrev_b32_e32 v150, 16, v102
	v_and_b32_e32 v151, 0xffff0000, v102
	v_lshlrev_b32_e32 v152, 16, v103
	v_and_b32_e32 v153, 0xffff0000, v103
	v_or_b32_e32 v139, s22, v140
	v_pk_fma_f32 v[4:5], v[154:155], v[150:151], v[4:5]
	v_pk_fma_f32 v[6:7], v[156:157], v[152:153], v[6:7]
	v_or_b32_e32 v139, s6, v139
	v_lshl_add_u32 v141, v139, 10, v146
	v_mul_f32_e32 v150, 0x3d372713, v4
	v_mul_f32_e32 v151, 0x3d372713, v5
	v_mul_f32_e32 v152, 0x3d372713, v6
	v_mul_f32_e32 v153, 0x3d372713, v7
	v_mul_f32_e32 v150, v4, v150
	v_mul_f32_e32 v151, v5, v151
	v_mul_f32_e32 v152, v6, v152
	v_mul_f32_e32 v153, v7, v153
	v_fma_f32 v150, v4, v150, v4
	v_fma_f32 v151, v5, v151, v5
	v_fma_f32 v152, v6, v152, v6
	v_fma_f32 v153, v7, v153, v7
	v_mul_f32_e32 v150, 0x3f4c422a, v150
	v_mul_f32_e32 v151, 0x3f4c422a, v151
	v_mul_f32_e32 v152, 0x3f4c422a, v152
	v_mul_f32_e32 v153, 0x3f4c422a, v153
	v_add_f32_e32 v150, v150, v150
	v_add_f32_e32 v151, v151, v151
	v_add_f32_e32 v152, v152, v152
	v_add_f32_e32 v153, v153, v153
	v_mul_f32_e32 v150, 0x3fb8aa3b, v150
	v_mul_f32_e32 v151, 0x3fb8aa3b, v151
	v_mul_f32_e32 v152, 0x3fb8aa3b, v152
	v_mul_f32_e32 v153, 0x3fb8aa3b, v153
	v_exp_f32_e32 v150, v150
	v_exp_f32_e32 v151, v151
	v_exp_f32_e32 v152, v152
	v_exp_f32_e32 v153, v153
	v_add_f32_e32 v150, 1.0, v150
	v_add_f32_e32 v151, 1.0, v151
	v_add_f32_e32 v152, 1.0, v152
	v_add_f32_e32 v153, 1.0, v153
	v_rcp_f32_e32 v150, v150
	v_rcp_f32_e32 v151, v151
	v_rcp_f32_e32 v152, v152
	v_rcp_f32_e32 v153, v153
	v_pk_mul_f32 v[4:5], v[4:5], 0.5 op_sel_hi:[1,0]
	v_pk_mul_f32 v[6:7], v[6:7], 0.5 op_sel_hi:[1,0]
	v_pk_fma_f32 v[150:151], v[150:151], 2.0, 1.0 op_sel_hi:[1,0,0] neg_lo:[1,0,0] neg_hi:[1,0,0]
	v_pk_fma_f32 v[152:153], v[152:153], 2.0, 1.0 op_sel_hi:[1,0,0] neg_lo:[1,0,0] neg_hi:[1,0,0]
	v_pk_add_f32 v[150:151], v[150:151], 1.0 op_sel_hi:[1,0]
	v_pk_add_f32 v[152:153], v[152:153], 1.0 op_sel_hi:[1,0]
	v_pk_mul_f32 v[4:5], v[4:5], v[150:151]
	v_pk_mul_f32 v[6:7], v[6:7], v[152:153]
	s_nop 0
	v_cvt_pk_bf16_f32 v4, v4, v5
	v_cvt_pk_bf16_f32 v5, v6, v7
	global_store_dwordx2 v141, v[4:5], s[78:79]
	s_mov_b64 s[4:5], -1
	s_and_b64 vcc, exec, s[8:9]
	s_cbranch_vccnz .LBB0_705
	s_andn2_b64 vcc, exec, s[10:11]
	s_cbranch_vccnz .LBB0_704
	s_barrier
	s_branch .LBB0_704
